# P5 branch-merge epilogue rewritten: GT/MACC scratch loads ring-buffered 7 slots ahead (dwordx4 sc1), no per-slot drain
# speedup vs baseline: 1.0234x; 1.0136x over previous
; __device__ __forceinline__ unsigned cvt_pk_bf16(float lo, float hi) { unsigned r; asm("v_cvt_pk_bf16_f32 %0, %1, %2" : "=v"(r) : "v"(lo), "v"(hi)); return r; }
; __device__ __forceinline__ float lo_bf(unsigned u) { return __uint_as_float(u << 16); }
; __device__ __forceinline__ float hi_bf(unsigned u) { return __uint_as_float(u & 0xffff0000u); }
;     __device__ __forceinline__ void operator()(f32x4 (&acc)[2][2][4][2], const GUnit& u, int wr, int wc, int fr, int fq, int tid) const {
;     ...
;         } else {
;             bf16_t* mp = (bf16_t*)MACC + (size_t)tid * 8;
;             bf16_t* op = O + (size_t)(u.pm * BM + wr * 64 + fr) * DM + u.pn * BM + wc * 32 + 8 * fq;
; #pragma unroll
;             for (int ai = 0; ai < 2; ++ai)
; #pragma unroll
;                 for (int bj = 0; bj < 2; ++bj)
; #pragma unroll
;                     for (int m = 0; m < 4; ++m) {
;                         const u32x4 g = ld_coh16(gp);
;                         u32x4 q = {0u, 0u, 0u, 0u}; if (sub != 1) q = ld_coh16(mp);
;                         f32x4 g0 = {lo_bf(g.x), hi_bf(g.x), lo_bf(g.y), hi_bf(g.y)}, g1 = {lo_bf(g.z), hi_bf(g.z), lo_bf(g.w), hi_bf(g.w)};
;                         f32x4 v0 = g0 * acc[ai][bj][m][0], v1 = g1 * acc[ai][bj][m][1];
;                         if (sub != 1) { v0 += (f32x4){lo_bf(q.x), hi_bf(q.x), lo_bf(q.y), hi_bf(q.y)}; v1 += (f32x4){lo_bf(q.z), hi_bf(q.z), lo_bf(q.w), hi_bf(q.w)}; }
;                         if (sub != 5) { u32x4 w; w.x = cvt_pk_bf16(v0[0], v0[1]); w.y = cvt_pk_bf16(v0[2], v0[3]); w.z = cvt_pk_bf16(v1[0], v1[1]); w.w = cvt_pk_bf16(v1[2], v1[3]); st_coh16(mp, w); }
;                         else { u32x4 w; w.x = cvt_pk_bf16(v0[0], v0[1]); w.y = cvt_pk_bf16(v0[2], v0[3]); w.z = cvt_pk_bf16(v1[0], v1[1]); w.w = cvt_pk_bf16(v1[2], v1[3]);
;                             *(u32x4*)(op + (size_t)(ai * HALF + m * 16) * DM + bj * HALF) = w; }
;                         gp += 4096; mp += 4096; asm volatile("" : "+v"(gp), "+v"(mp) :: "memory"); }
.LBB0_577:
	v_mov_b32_e32 v128, v181
	v_mov_b32_e32 v136, v177
	v_mov_b32_e32 v143, v252
	s_bitcmp1_b32 s96, 0
	s_cselect_b64 s[14:15], -1, 0
	v_ashrrev_i32_e32 v129, 31, v128
	v_lshl_add_u64 v[150:151], v[128:129], 4, s[22:23]
	s_mov_b64 s[12:13], -1
	s_and_b64 vcc, exec, s[14:15]
	v_mov_b64_e32 v[250:251], v[182:183]
	s_cbranch_vccz .LBB0_679
	v_readlane_b32 s12, v255, 36
	v_readlane_b32 s13, v255, 37
	v_readlane_b32 s54, v255, 19
	v_readlane_b32 s55, v255, 20
	v_lshlrev_b32_e32 v129, 4, v128
	s_lshl_b32 s36, s90, 8
	v_readlane_b32 s39, v255, 38
	v_lshlrev_b32_e32 v130, 4, v128
	s_nop 1
	s_add_i32 s36, s36, s39
	v_add_u32_e32 v131, s36, v143
	v_lshlrev_b32_e32 v131, 12, v131
	s_lshl_b32 s36, s97, 9
	s_lshl_b32 s39, s20, 1
	s_add_i32 s36, s36, s39
	v_lshl_add_u32 v138, v136, 4, s36
	v_add_u32_e32 v131, v131, v138
	s_cmp_eq_u32 s96, 1
	s_cbranch_scc1 .Lbe_sub1
	s_cmp_eq_u32 s96, 5
	s_cbranch_scc1 .Lbe_sub5
	global_load_dwordx4 v[188:191], v129, s[22:23] sc1
	global_load_dwordx4 v[192:195], v129, s[12:13] sc1
	v_add_u32_e32 v129, 0x2000, v129
	global_load_dwordx4 v[196:199], v129, s[22:23] sc1
	global_load_dwordx4 v[200:203], v129, s[12:13] sc1
	v_add_u32_e32 v129, 0x2000, v129
	global_load_dwordx4 v[204:207], v129, s[22:23] sc1
	global_load_dwordx4 v[208:211], v129, s[12:13] sc1
	v_add_u32_e32 v129, 0x2000, v129
	global_load_dwordx4 v[212:215], v129, s[22:23] sc1
	global_load_dwordx4 v[216:219], v129, s[12:13] sc1
	v_add_u32_e32 v129, 0x2000, v129
	global_load_dwordx4 v[220:223], v129, s[22:23] sc1
	global_load_dwordx4 v[224:227], v129, s[12:13] sc1
	v_add_u32_e32 v129, 0x2000, v129
	global_load_dwordx4 v[228:231], v129, s[22:23] sc1
	global_load_dwordx4 v[232:235], v129, s[12:13] sc1
	v_add_u32_e32 v129, 0x2000, v129
	global_load_dwordx4 v[236:239], v129, s[22:23] sc1
	global_load_dwordx4 v[240:243], v129, s[12:13] sc1
	v_add_u32_e32 v129, 0x2000, v129
	s_waitcnt vmcnt(12)
	v_lshlrev_b32_e32 v152, 16, v188
	v_and_b32_e32 v153, 0xffff0000, v188
	v_lshlrev_b32_e32 v154, 16, v189
	v_and_b32_e32 v155, 0xffff0000, v189
	v_lshlrev_b32_e32 v156, 16, v190
	v_and_b32_e32 v157, 0xffff0000, v190
	v_lshlrev_b32_e32 v158, 16, v191
	v_and_b32_e32 v159, 0xffff0000, v191
	v_pk_mul_f32 v[124:125], v[124:125], v[152:153]
	v_pk_mul_f32 v[126:127], v[126:127], v[154:155]
	v_pk_mul_f32 v[120:121], v[120:121], v[156:157]
	v_pk_mul_f32 v[122:123], v[122:123], v[158:159]
	v_lshlrev_b32_e32 v152, 16, v192
	v_and_b32_e32 v153, 0xffff0000, v192
	v_lshlrev_b32_e32 v154, 16, v193
	v_and_b32_e32 v155, 0xffff0000, v193
	v_lshlrev_b32_e32 v156, 16, v194
	v_and_b32_e32 v157, 0xffff0000, v194
	v_lshlrev_b32_e32 v158, 16, v195
	v_and_b32_e32 v159, 0xffff0000, v195
	v_pk_add_f32 v[124:125], v[124:125], v[152:153]
	v_pk_add_f32 v[126:127], v[126:127], v[154:155]
	v_pk_add_f32 v[120:121], v[120:121], v[156:157]
	v_pk_add_f32 v[122:123], v[122:123], v[158:159]
	v_cvt_pk_bf16_f32 v132, v124, v125
	v_cvt_pk_bf16_f32 v133, v126, v127
	v_cvt_pk_bf16_f32 v134, v120, v121
	v_cvt_pk_bf16_f32 v135, v122, v123
	global_store_dwordx4 v130, v[132:135], s[12:13] sc1
	v_add_u32_e32 v130, 0x2000, v130
	global_load_dwordx4 v[188:191], v129, s[22:23] sc1
	global_load_dwordx4 v[192:195], v129, s[12:13] sc1
	v_add_u32_e32 v129, 0x2000, v129
	s_waitcnt vmcnt(13)
	v_lshlrev_b32_e32 v152, 16, v196
	v_and_b32_e32 v153, 0xffff0000, v196
	v_lshlrev_b32_e32 v154, 16, v197
	v_and_b32_e32 v155, 0xffff0000, v197
	v_lshlrev_b32_e32 v156, 16, v198
	v_and_b32_e32 v157, 0xffff0000, v198
	v_lshlrev_b32_e32 v158, 16, v199
	v_and_b32_e32 v159, 0xffff0000, v199
	v_pk_mul_f32 v[116:117], v[116:117], v[152:153]
	v_pk_mul_f32 v[118:119], v[118:119], v[154:155]
	v_pk_mul_f32 v[112:113], v[112:113], v[156:157]
	v_pk_mul_f32 v[114:115], v[114:115], v[158:159]
	v_lshlrev_b32_e32 v152, 16, v200
	v_and_b32_e32 v153, 0xffff0000, v200
	v_lshlrev_b32_e32 v154, 16, v201
	v_and_b32_e32 v155, 0xffff0000, v201
	v_lshlrev_b32_e32 v156, 16, v202
	v_and_b32_e32 v157, 0xffff0000, v202
	v_lshlrev_b32_e32 v158, 16, v203
	v_and_b32_e32 v159, 0xffff0000, v203
	v_pk_add_f32 v[116:117], v[116:117], v[152:153]
	v_pk_add_f32 v[118:119], v[118:119], v[154:155]
	v_pk_add_f32 v[112:113], v[112:113], v[156:157]
	v_pk_add_f32 v[114:115], v[114:115], v[158:159]
	v_cvt_pk_bf16_f32 v132, v116, v117
	v_cvt_pk_bf16_f32 v133, v118, v119
	v_cvt_pk_bf16_f32 v134, v112, v113
	v_cvt_pk_bf16_f32 v135, v114, v115
	global_store_dwordx4 v130, v[132:135], s[12:13] sc1
	v_add_u32_e32 v130, 0x2000, v130
	global_load_dwordx4 v[196:199], v129, s[22:23] sc1
	global_load_dwordx4 v[200:203], v129, s[12:13] sc1
	v_add_u32_e32 v129, 0x2000, v129
	s_waitcnt vmcnt(14)
	v_lshlrev_b32_e32 v152, 16, v204
	v_and_b32_e32 v153, 0xffff0000, v204
	v_lshlrev_b32_e32 v154, 16, v205
	v_and_b32_e32 v155, 0xffff0000, v205
	v_lshlrev_b32_e32 v156, 16, v206
	v_and_b32_e32 v157, 0xffff0000, v206
	v_lshlrev_b32_e32 v158, 16, v207
	v_and_b32_e32 v159, 0xffff0000, v207
	v_pk_mul_f32 v[108:109], v[108:109], v[152:153]
	v_pk_mul_f32 v[110:111], v[110:111], v[154:155]
	v_pk_mul_f32 v[104:105], v[104:105], v[156:157]
	v_pk_mul_f32 v[106:107], v[106:107], v[158:159]
	v_lshlrev_b32_e32 v152, 16, v208
	v_and_b32_e32 v153, 0xffff0000, v208
	v_lshlrev_b32_e32 v154, 16, v209
	v_and_b32_e32 v155, 0xffff0000, v209
	v_lshlrev_b32_e32 v156, 16, v210
	v_and_b32_e32 v157, 0xffff0000, v210
	v_lshlrev_b32_e32 v158, 16, v211
	v_and_b32_e32 v159, 0xffff0000, v211
	v_pk_add_f32 v[108:109], v[108:109], v[152:153]
	v_pk_add_f32 v[110:111], v[110:111], v[154:155]
	v_pk_add_f32 v[104:105], v[104:105], v[156:157]
	v_pk_add_f32 v[106:107], v[106:107], v[158:159]
	v_cvt_pk_bf16_f32 v132, v108, v109
	v_cvt_pk_bf16_f32 v133, v110, v111
	v_cvt_pk_bf16_f32 v134, v104, v105
	v_cvt_pk_bf16_f32 v135, v106, v107
	global_store_dwordx4 v130, v[132:135], s[12:13] sc1
	v_add_u32_e32 v130, 0x2000, v130
	global_load_dwordx4 v[204:207], v129, s[22:23] sc1
	global_load_dwordx4 v[208:211], v129, s[12:13] sc1
	v_add_u32_e32 v129, 0x2000, v129
	s_waitcnt vmcnt(15)
; __device__ __forceinline__ unsigned cvt_pk_bf16(float lo, float hi) { unsigned r; asm("v_cvt_pk_bf16_f32 %0, %1, %2" : "=v"(r) : "v"(lo), "v"(hi)); return r; }
; __device__ __forceinline__ float lo_bf(unsigned u) { return __uint_as_float(u << 16); }
; __device__ __forceinline__ float hi_bf(unsigned u) { return __uint_as_float(u & 0xffff0000u); }
;     __device__ __forceinline__ void operator()(f32x4 (&acc)[2][2][4][2], const GUnit& u, int wr, int wc, int fr, int fq, int tid) const {
;     ...
;                     for (int m = 0; m < 4; ++m) {
;                         const u32x4 g = ld_coh16(gp);
;                         u32x4 q = {0u, 0u, 0u, 0u}; if (sub != 1) q = ld_coh16(mp);
;                         f32x4 g0 = {lo_bf(g.x), hi_bf(g.x), lo_bf(g.y), hi_bf(g.y)}, g1 = {lo_bf(g.z), hi_bf(g.z), lo_bf(g.w), hi_bf(g.w)};
;                         f32x4 v0 = g0 * acc[ai][bj][m][0], v1 = g1 * acc[ai][bj][m][1];
;                         if (sub != 1) { v0 += (f32x4){lo_bf(q.x), hi_bf(q.x), lo_bf(q.y), hi_bf(q.y)}; v1 += (f32x4){lo_bf(q.z), hi_bf(q.z), lo_bf(q.w), hi_bf(q.w)}; }
;                         if (sub != 5) { u32x4 w; w.x = cvt_pk_bf16(v0[0], v0[1]); w.y = cvt_pk_bf16(v0[2], v0[3]); w.z = cvt_pk_bf16(v1[0], v1[1]); w.w = cvt_pk_bf16(v1[2], v1[3]); st_coh16(mp, w); }
;                         else { u32x4 w; w.x = cvt_pk_bf16(v0[0], v0[1]); w.y = cvt_pk_bf16(v0[2], v0[3]); w.z = cvt_pk_bf16(v1[0], v1[1]); w.w = cvt_pk_bf16(v1[2], v1[3]);
;                             *(u32x4*)(op + (size_t)(ai * HALF + m * 16) * DM + bj * HALF) = w; }
;                         gp += 4096; mp += 4096; asm volatile("" : "+v"(gp), "+v"(mp) :: "memory"); }
	v_lshlrev_b32_e32 v152, 16, v212
	v_and_b32_e32 v153, 0xffff0000, v212
	v_lshlrev_b32_e32 v154, 16, v213
	v_and_b32_e32 v155, 0xffff0000, v213
	v_lshlrev_b32_e32 v156, 16, v214
	v_and_b32_e32 v157, 0xffff0000, v214
	v_lshlrev_b32_e32 v158, 16, v215
	v_and_b32_e32 v159, 0xffff0000, v215
	v_pk_mul_f32 v[100:101], v[100:101], v[152:153]
	v_pk_mul_f32 v[102:103], v[102:103], v[154:155]
	v_pk_mul_f32 v[96:97], v[96:97], v[156:157]
	v_pk_mul_f32 v[98:99], v[98:99], v[158:159]
	v_lshlrev_b32_e32 v152, 16, v216
	v_and_b32_e32 v153, 0xffff0000, v216
	v_lshlrev_b32_e32 v154, 16, v217
	v_and_b32_e32 v155, 0xffff0000, v217
	v_lshlrev_b32_e32 v156, 16, v218
	v_and_b32_e32 v157, 0xffff0000, v218
	v_lshlrev_b32_e32 v158, 16, v219
	v_and_b32_e32 v159, 0xffff0000, v219
	v_pk_add_f32 v[100:101], v[100:101], v[152:153]
	v_pk_add_f32 v[102:103], v[102:103], v[154:155]
	v_pk_add_f32 v[96:97], v[96:97], v[156:157]
	v_pk_add_f32 v[98:99], v[98:99], v[158:159]
	v_cvt_pk_bf16_f32 v132, v100, v101
	v_cvt_pk_bf16_f32 v133, v102, v103
	v_cvt_pk_bf16_f32 v134, v96, v97
	v_cvt_pk_bf16_f32 v135, v98, v99
	global_store_dwordx4 v130, v[132:135], s[12:13] sc1
	v_add_u32_e32 v130, 0x2000, v130
	global_load_dwordx4 v[212:215], v129, s[22:23] sc1
	global_load_dwordx4 v[216:219], v129, s[12:13] sc1
	v_add_u32_e32 v129, 0x2000, v129
	s_waitcnt vmcnt(16)
	v_lshlrev_b32_e32 v152, 16, v220
	v_and_b32_e32 v153, 0xffff0000, v220
	v_lshlrev_b32_e32 v154, 16, v221
	v_and_b32_e32 v155, 0xffff0000, v221
	v_lshlrev_b32_e32 v156, 16, v222
	v_and_b32_e32 v157, 0xffff0000, v222
	v_lshlrev_b32_e32 v158, 16, v223
	v_and_b32_e32 v159, 0xffff0000, v223
	v_pk_mul_f32 v[92:93], v[92:93], v[152:153]
	v_pk_mul_f32 v[94:95], v[94:95], v[154:155]
	v_pk_mul_f32 v[88:89], v[88:89], v[156:157]
	v_pk_mul_f32 v[90:91], v[90:91], v[158:159]
	v_lshlrev_b32_e32 v152, 16, v224
	v_and_b32_e32 v153, 0xffff0000, v224
	v_lshlrev_b32_e32 v154, 16, v225
	v_and_b32_e32 v155, 0xffff0000, v225
	v_lshlrev_b32_e32 v156, 16, v226
	v_and_b32_e32 v157, 0xffff0000, v226
	v_lshlrev_b32_e32 v158, 16, v227
	v_and_b32_e32 v159, 0xffff0000, v227
	v_pk_add_f32 v[92:93], v[92:93], v[152:153]
	v_pk_add_f32 v[94:95], v[94:95], v[154:155]
	v_pk_add_f32 v[88:89], v[88:89], v[156:157]
	v_pk_add_f32 v[90:91], v[90:91], v[158:159]
	v_cvt_pk_bf16_f32 v132, v92, v93
	v_cvt_pk_bf16_f32 v133, v94, v95
	v_cvt_pk_bf16_f32 v134, v88, v89
	v_cvt_pk_bf16_f32 v135, v90, v91
	global_store_dwordx4 v130, v[132:135], s[12:13] sc1
	v_add_u32_e32 v130, 0x2000, v130
	global_load_dwordx4 v[220:223], v129, s[22:23] sc1
	global_load_dwordx4 v[224:227], v129, s[12:13] sc1
	v_add_u32_e32 v129, 0x2000, v129
	s_waitcnt vmcnt(17)
	v_lshlrev_b32_e32 v152, 16, v228
	v_and_b32_e32 v153, 0xffff0000, v228
	v_lshlrev_b32_e32 v154, 16, v229
	v_and_b32_e32 v155, 0xffff0000, v229
	v_lshlrev_b32_e32 v156, 16, v230
	v_and_b32_e32 v157, 0xffff0000, v230
	v_lshlrev_b32_e32 v158, 16, v231
	v_and_b32_e32 v159, 0xffff0000, v231
	v_pk_mul_f32 v[84:85], v[84:85], v[152:153]
	v_pk_mul_f32 v[86:87], v[86:87], v[154:155]
	v_pk_mul_f32 v[80:81], v[80:81], v[156:157]
	v_pk_mul_f32 v[82:83], v[82:83], v[158:159]
	v_lshlrev_b32_e32 v152, 16, v232
	v_and_b32_e32 v153, 0xffff0000, v232
	v_lshlrev_b32_e32 v154, 16, v233
	v_and_b32_e32 v155, 0xffff0000, v233
	v_lshlrev_b32_e32 v156, 16, v234
	v_and_b32_e32 v157, 0xffff0000, v234
	v_lshlrev_b32_e32 v158, 16, v235
	v_and_b32_e32 v159, 0xffff0000, v235
	v_pk_add_f32 v[84:85], v[84:85], v[152:153]
	v_pk_add_f32 v[86:87], v[86:87], v[154:155]
	v_pk_add_f32 v[80:81], v[80:81], v[156:157]
	v_pk_add_f32 v[82:83], v[82:83], v[158:159]
	v_cvt_pk_bf16_f32 v132, v84, v85
	v_cvt_pk_bf16_f32 v133, v86, v87
	v_cvt_pk_bf16_f32 v134, v80, v81
	v_cvt_pk_bf16_f32 v135, v82, v83
	global_store_dwordx4 v130, v[132:135], s[12:13] sc1
	v_add_u32_e32 v130, 0x2000, v130
	global_load_dwordx4 v[228:231], v129, s[22:23] sc1
	global_load_dwordx4 v[232:235], v129, s[12:13] sc1
	v_add_u32_e32 v129, 0x2000, v129
	s_waitcnt vmcnt(18)
	v_lshlrev_b32_e32 v152, 16, v236
	v_and_b32_e32 v153, 0xffff0000, v236
	v_lshlrev_b32_e32 v154, 16, v237
	v_and_b32_e32 v155, 0xffff0000, v237
	v_lshlrev_b32_e32 v156, 16, v238
	v_and_b32_e32 v157, 0xffff0000, v238
	v_lshlrev_b32_e32 v158, 16, v239
	v_and_b32_e32 v159, 0xffff0000, v239
	v_pk_mul_f32 v[76:77], v[76:77], v[152:153]
	v_pk_mul_f32 v[78:79], v[78:79], v[154:155]
	v_pk_mul_f32 v[72:73], v[72:73], v[156:157]
	v_pk_mul_f32 v[74:75], v[74:75], v[158:159]
	v_lshlrev_b32_e32 v152, 16, v240
	v_and_b32_e32 v153, 0xffff0000, v240
	v_lshlrev_b32_e32 v154, 16, v241
	v_and_b32_e32 v155, 0xffff0000, v241
	v_lshlrev_b32_e32 v156, 16, v242
	v_and_b32_e32 v157, 0xffff0000, v242
	v_lshlrev_b32_e32 v158, 16, v243
	v_and_b32_e32 v159, 0xffff0000, v243
	v_pk_add_f32 v[76:77], v[76:77], v[152:153]
	v_pk_add_f32 v[78:79], v[78:79], v[154:155]
	v_pk_add_f32 v[72:73], v[72:73], v[156:157]
	v_pk_add_f32 v[74:75], v[74:75], v[158:159]
	v_cvt_pk_bf16_f32 v132, v76, v77
	v_cvt_pk_bf16_f32 v133, v78, v79
	v_cvt_pk_bf16_f32 v134, v72, v73
	v_cvt_pk_bf16_f32 v135, v74, v75
	global_store_dwordx4 v130, v[132:135], s[12:13] sc1
	v_add_u32_e32 v130, 0x2000, v130
	global_load_dwordx4 v[236:239], v129, s[22:23] sc1
	global_load_dwordx4 v[240:243], v129, s[12:13] sc1
	v_add_u32_e32 v129, 0x2000, v129
	s_waitcnt vmcnt(18)
; __device__ __forceinline__ unsigned cvt_pk_bf16(float lo, float hi) { unsigned r; asm("v_cvt_pk_bf16_f32 %0, %1, %2" : "=v"(r) : "v"(lo), "v"(hi)); return r; }
; __device__ __forceinline__ float lo_bf(unsigned u) { return __uint_as_float(u << 16); }
; __device__ __forceinline__ float hi_bf(unsigned u) { return __uint_as_float(u & 0xffff0000u); }
;     __device__ __forceinline__ void operator()(f32x4 (&acc)[2][2][4][2], const GUnit& u, int wr, int wc, int fr, int fq, int tid) const {
;     ...
;                     for (int m = 0; m < 4; ++m) {
;                         const u32x4 g = ld_coh16(gp);
;                         u32x4 q = {0u, 0u, 0u, 0u}; if (sub != 1) q = ld_coh16(mp);
;                         f32x4 g0 = {lo_bf(g.x), hi_bf(g.x), lo_bf(g.y), hi_bf(g.y)}, g1 = {lo_bf(g.z), hi_bf(g.z), lo_bf(g.w), hi_bf(g.w)};
;                         f32x4 v0 = g0 * acc[ai][bj][m][0], v1 = g1 * acc[ai][bj][m][1];
;                         if (sub != 1) { v0 += (f32x4){lo_bf(q.x), hi_bf(q.x), lo_bf(q.y), hi_bf(q.y)}; v1 += (f32x4){lo_bf(q.z), hi_bf(q.z), lo_bf(q.w), hi_bf(q.w)}; }
;                         if (sub != 5) { u32x4 w; w.x = cvt_pk_bf16(v0[0], v0[1]); w.y = cvt_pk_bf16(v0[2], v0[3]); w.z = cvt_pk_bf16(v1[0], v1[1]); w.w = cvt_pk_bf16(v1[2], v1[3]); st_coh16(mp, w); }
;                         else { u32x4 w; w.x = cvt_pk_bf16(v0[0], v0[1]); w.y = cvt_pk_bf16(v0[2], v0[3]); w.z = cvt_pk_bf16(v1[0], v1[1]); w.w = cvt_pk_bf16(v1[2], v1[3]);
;                             *(u32x4*)(op + (size_t)(ai * HALF + m * 16) * DM + bj * HALF) = w; }
;                         gp += 4096; mp += 4096; asm volatile("" : "+v"(gp), "+v"(mp) :: "memory"); }
	v_lshlrev_b32_e32 v152, 16, v188
	v_and_b32_e32 v153, 0xffff0000, v188
	v_lshlrev_b32_e32 v154, 16, v189
	v_and_b32_e32 v155, 0xffff0000, v189
	v_lshlrev_b32_e32 v156, 16, v190
	v_and_b32_e32 v157, 0xffff0000, v190
	v_lshlrev_b32_e32 v158, 16, v191
	v_and_b32_e32 v159, 0xffff0000, v191
	v_pk_mul_f32 v[68:69], v[68:69], v[152:153]
	v_pk_mul_f32 v[70:71], v[70:71], v[154:155]
	v_pk_mul_f32 v[64:65], v[64:65], v[156:157]
	v_pk_mul_f32 v[66:67], v[66:67], v[158:159]
	v_lshlrev_b32_e32 v152, 16, v192
	v_and_b32_e32 v153, 0xffff0000, v192
	v_lshlrev_b32_e32 v154, 16, v193
	v_and_b32_e32 v155, 0xffff0000, v193
	v_lshlrev_b32_e32 v156, 16, v194
	v_and_b32_e32 v157, 0xffff0000, v194
	v_lshlrev_b32_e32 v158, 16, v195
	v_and_b32_e32 v159, 0xffff0000, v195
	v_pk_add_f32 v[68:69], v[68:69], v[152:153]
	v_pk_add_f32 v[70:71], v[70:71], v[154:155]
	v_pk_add_f32 v[64:65], v[64:65], v[156:157]
	v_pk_add_f32 v[66:67], v[66:67], v[158:159]
	v_cvt_pk_bf16_f32 v132, v68, v69
	v_cvt_pk_bf16_f32 v133, v70, v71
	v_cvt_pk_bf16_f32 v134, v64, v65
	v_cvt_pk_bf16_f32 v135, v66, v67
	global_store_dwordx4 v130, v[132:135], s[12:13] sc1
	v_add_u32_e32 v130, 0x2000, v130
	global_load_dwordx4 v[188:191], v129, s[22:23] sc1
	global_load_dwordx4 v[192:195], v129, s[12:13] sc1
	v_add_u32_e32 v129, 0x2000, v129
	s_waitcnt vmcnt(18)
	v_lshlrev_b32_e32 v152, 16, v196
	v_and_b32_e32 v153, 0xffff0000, v196
	v_lshlrev_b32_e32 v154, 16, v197
	v_and_b32_e32 v155, 0xffff0000, v197
	v_lshlrev_b32_e32 v156, 16, v198
	v_and_b32_e32 v157, 0xffff0000, v198
	v_lshlrev_b32_e32 v158, 16, v199
	v_and_b32_e32 v159, 0xffff0000, v199
	v_pk_mul_f32 v[60:61], v[60:61], v[152:153]
	v_pk_mul_f32 v[62:63], v[62:63], v[154:155]
	v_pk_mul_f32 v[56:57], v[56:57], v[156:157]
	v_pk_mul_f32 v[58:59], v[58:59], v[158:159]
	v_lshlrev_b32_e32 v152, 16, v200
	v_and_b32_e32 v153, 0xffff0000, v200
	v_lshlrev_b32_e32 v154, 16, v201
	v_and_b32_e32 v155, 0xffff0000, v201
	v_lshlrev_b32_e32 v156, 16, v202
	v_and_b32_e32 v157, 0xffff0000, v202
	v_lshlrev_b32_e32 v158, 16, v203
	v_and_b32_e32 v159, 0xffff0000, v203
	v_pk_add_f32 v[60:61], v[60:61], v[152:153]
	v_pk_add_f32 v[62:63], v[62:63], v[154:155]
	v_pk_add_f32 v[56:57], v[56:57], v[156:157]
	v_pk_add_f32 v[58:59], v[58:59], v[158:159]
	v_cvt_pk_bf16_f32 v132, v60, v61
	v_cvt_pk_bf16_f32 v133, v62, v63
	v_cvt_pk_bf16_f32 v134, v56, v57
	v_cvt_pk_bf16_f32 v135, v58, v59
	global_store_dwordx4 v130, v[132:135], s[12:13] sc1
	v_add_u32_e32 v130, 0x2000, v130
	global_load_dwordx4 v[196:199], v129, s[22:23] sc1
	global_load_dwordx4 v[200:203], v129, s[12:13] sc1
	v_add_u32_e32 v129, 0x2000, v129
	s_waitcnt vmcnt(18)
	v_lshlrev_b32_e32 v152, 16, v204
	v_and_b32_e32 v153, 0xffff0000, v204
	v_lshlrev_b32_e32 v154, 16, v205
	v_and_b32_e32 v155, 0xffff0000, v205
	v_lshlrev_b32_e32 v156, 16, v206
	v_and_b32_e32 v157, 0xffff0000, v206
	v_lshlrev_b32_e32 v158, 16, v207
	v_and_b32_e32 v159, 0xffff0000, v207
	v_pk_mul_f32 v[52:53], v[52:53], v[152:153]
	v_pk_mul_f32 v[54:55], v[54:55], v[154:155]
	v_pk_mul_f32 v[48:49], v[48:49], v[156:157]
	v_pk_mul_f32 v[50:51], v[50:51], v[158:159]
	v_lshlrev_b32_e32 v152, 16, v208
	v_and_b32_e32 v153, 0xffff0000, v208
	v_lshlrev_b32_e32 v154, 16, v209
	v_and_b32_e32 v155, 0xffff0000, v209
	v_lshlrev_b32_e32 v156, 16, v210
	v_and_b32_e32 v157, 0xffff0000, v210
	v_lshlrev_b32_e32 v158, 16, v211
	v_and_b32_e32 v159, 0xffff0000, v211
	v_pk_add_f32 v[52:53], v[52:53], v[152:153]
	v_pk_add_f32 v[54:55], v[54:55], v[154:155]
	v_pk_add_f32 v[48:49], v[48:49], v[156:157]
	v_pk_add_f32 v[50:51], v[50:51], v[158:159]
	v_cvt_pk_bf16_f32 v132, v52, v53
	v_cvt_pk_bf16_f32 v133, v54, v55
	v_cvt_pk_bf16_f32 v134, v48, v49
	v_cvt_pk_bf16_f32 v135, v50, v51
	global_store_dwordx4 v130, v[132:135], s[12:13] sc1
	v_add_u32_e32 v130, 0x2000, v130
	s_waitcnt vmcnt(16)
	v_lshlrev_b32_e32 v152, 16, v212
	v_and_b32_e32 v153, 0xffff0000, v212
	v_lshlrev_b32_e32 v154, 16, v213
	v_and_b32_e32 v155, 0xffff0000, v213
	v_lshlrev_b32_e32 v156, 16, v214
	v_and_b32_e32 v157, 0xffff0000, v214
	v_lshlrev_b32_e32 v158, 16, v215
	v_and_b32_e32 v159, 0xffff0000, v215
	v_pk_mul_f32 v[44:45], v[44:45], v[152:153]
	v_pk_mul_f32 v[46:47], v[46:47], v[154:155]
	v_pk_mul_f32 v[40:41], v[40:41], v[156:157]
	v_pk_mul_f32 v[42:43], v[42:43], v[158:159]
	v_lshlrev_b32_e32 v152, 16, v216
	v_and_b32_e32 v153, 0xffff0000, v216
	v_lshlrev_b32_e32 v154, 16, v217
	v_and_b32_e32 v155, 0xffff0000, v217
	v_lshlrev_b32_e32 v156, 16, v218
	v_and_b32_e32 v157, 0xffff0000, v218
	v_lshlrev_b32_e32 v158, 16, v219
	v_and_b32_e32 v159, 0xffff0000, v219
	v_pk_add_f32 v[44:45], v[44:45], v[152:153]
	v_pk_add_f32 v[46:47], v[46:47], v[154:155]
	v_pk_add_f32 v[40:41], v[40:41], v[156:157]
	v_pk_add_f32 v[42:43], v[42:43], v[158:159]
	v_cvt_pk_bf16_f32 v132, v44, v45
	v_cvt_pk_bf16_f32 v133, v46, v47
	v_cvt_pk_bf16_f32 v134, v40, v41
	v_cvt_pk_bf16_f32 v135, v42, v43
	global_store_dwordx4 v130, v[132:135], s[12:13] sc1
	v_add_u32_e32 v130, 0x2000, v130
	s_waitcnt vmcnt(14)
	v_lshlrev_b32_e32 v152, 16, v220
	v_and_b32_e32 v153, 0xffff0000, v220
	v_lshlrev_b32_e32 v154, 16, v221
	v_and_b32_e32 v155, 0xffff0000, v221
	v_lshlrev_b32_e32 v156, 16, v222
	v_and_b32_e32 v157, 0xffff0000, v222
	v_lshlrev_b32_e32 v158, 16, v223
	v_and_b32_e32 v159, 0xffff0000, v223
	v_pk_mul_f32 v[36:37], v[36:37], v[152:153]
	v_pk_mul_f32 v[38:39], v[38:39], v[154:155]
	v_pk_mul_f32 v[32:33], v[32:33], v[156:157]
	v_pk_mul_f32 v[34:35], v[34:35], v[158:159]
	v_lshlrev_b32_e32 v152, 16, v224
	v_and_b32_e32 v153, 0xffff0000, v224
	v_lshlrev_b32_e32 v154, 16, v225
	v_and_b32_e32 v155, 0xffff0000, v225
	v_lshlrev_b32_e32 v156, 16, v226
	v_and_b32_e32 v157, 0xffff0000, v226
	v_lshlrev_b32_e32 v158, 16, v227
	v_and_b32_e32 v159, 0xffff0000, v227
	v_pk_add_f32 v[36:37], v[36:37], v[152:153]
	v_pk_add_f32 v[38:39], v[38:39], v[154:155]
	v_pk_add_f32 v[32:33], v[32:33], v[156:157]
	v_pk_add_f32 v[34:35], v[34:35], v[158:159]
	v_cvt_pk_bf16_f32 v132, v36, v37
	v_cvt_pk_bf16_f32 v133, v38, v39
	v_cvt_pk_bf16_f32 v134, v32, v33
	v_cvt_pk_bf16_f32 v135, v34, v35
	global_store_dwordx4 v130, v[132:135], s[12:13] sc1
	v_add_u32_e32 v130, 0x2000, v130
	s_waitcnt vmcnt(12)
; __device__ __forceinline__ unsigned cvt_pk_bf16(float lo, float hi) { unsigned r; asm("v_cvt_pk_bf16_f32 %0, %1, %2" : "=v"(r) : "v"(lo), "v"(hi)); return r; }
; __device__ __forceinline__ float lo_bf(unsigned u) { return __uint_as_float(u << 16); }
; __device__ __forceinline__ float hi_bf(unsigned u) { return __uint_as_float(u & 0xffff0000u); }
;     __device__ __forceinline__ void operator()(f32x4 (&acc)[2][2][4][2], const GUnit& u, int wr, int wc, int fr, int fq, int tid) const {
;     ...
;                     for (int m = 0; m < 4; ++m) {
;                         const u32x4 g = ld_coh16(gp);
;                         u32x4 q = {0u, 0u, 0u, 0u}; if (sub != 1) q = ld_coh16(mp);
;                         f32x4 g0 = {lo_bf(g.x), hi_bf(g.x), lo_bf(g.y), hi_bf(g.y)}, g1 = {lo_bf(g.z), hi_bf(g.z), lo_bf(g.w), hi_bf(g.w)};
;                         f32x4 v0 = g0 * acc[ai][bj][m][0], v1 = g1 * acc[ai][bj][m][1];
;                         if (sub != 1) { v0 += (f32x4){lo_bf(q.x), hi_bf(q.x), lo_bf(q.y), hi_bf(q.y)}; v1 += (f32x4){lo_bf(q.z), hi_bf(q.z), lo_bf(q.w), hi_bf(q.w)}; }
;                         if (sub != 5) { u32x4 w; w.x = cvt_pk_bf16(v0[0], v0[1]); w.y = cvt_pk_bf16(v0[2], v0[3]); w.z = cvt_pk_bf16(v1[0], v1[1]); w.w = cvt_pk_bf16(v1[2], v1[3]); st_coh16(mp, w); }
;                         else { u32x4 w; w.x = cvt_pk_bf16(v0[0], v0[1]); w.y = cvt_pk_bf16(v0[2], v0[3]); w.z = cvt_pk_bf16(v1[0], v1[1]); w.w = cvt_pk_bf16(v1[2], v1[3]);
;                             *(u32x4*)(op + (size_t)(ai * HALF + m * 16) * DM + bj * HALF) = w; }
;                         gp += 4096; mp += 4096; asm volatile("" : "+v"(gp), "+v"(mp) :: "memory"); }
	v_lshlrev_b32_e32 v152, 16, v228
	v_and_b32_e32 v153, 0xffff0000, v228
	v_lshlrev_b32_e32 v154, 16, v229
	v_and_b32_e32 v155, 0xffff0000, v229
	v_lshlrev_b32_e32 v156, 16, v230
	v_and_b32_e32 v157, 0xffff0000, v230
	v_lshlrev_b32_e32 v158, 16, v231
	v_and_b32_e32 v159, 0xffff0000, v231
	v_pk_mul_f32 v[28:29], v[28:29], v[152:153]
	v_pk_mul_f32 v[30:31], v[30:31], v[154:155]
	v_pk_mul_f32 v[24:25], v[24:25], v[156:157]
	v_pk_mul_f32 v[26:27], v[26:27], v[158:159]
	v_lshlrev_b32_e32 v152, 16, v232
	v_and_b32_e32 v153, 0xffff0000, v232
	v_lshlrev_b32_e32 v154, 16, v233
	v_and_b32_e32 v155, 0xffff0000, v233
	v_lshlrev_b32_e32 v156, 16, v234
	v_and_b32_e32 v157, 0xffff0000, v234
	v_lshlrev_b32_e32 v158, 16, v235
	v_and_b32_e32 v159, 0xffff0000, v235
	v_pk_add_f32 v[28:29], v[28:29], v[152:153]
	v_pk_add_f32 v[30:31], v[30:31], v[154:155]
	v_pk_add_f32 v[24:25], v[24:25], v[156:157]
	v_pk_add_f32 v[26:27], v[26:27], v[158:159]
	v_cvt_pk_bf16_f32 v132, v28, v29
	v_cvt_pk_bf16_f32 v133, v30, v31
	v_cvt_pk_bf16_f32 v134, v24, v25
	v_cvt_pk_bf16_f32 v135, v26, v27
	global_store_dwordx4 v130, v[132:135], s[12:13] sc1
	v_add_u32_e32 v130, 0x2000, v130
	s_waitcnt vmcnt(10)
	v_lshlrev_b32_e32 v152, 16, v236
	v_and_b32_e32 v153, 0xffff0000, v236
	v_lshlrev_b32_e32 v154, 16, v237
	v_and_b32_e32 v155, 0xffff0000, v237
	v_lshlrev_b32_e32 v156, 16, v238
	v_and_b32_e32 v157, 0xffff0000, v238
	v_lshlrev_b32_e32 v158, 16, v239
	v_and_b32_e32 v159, 0xffff0000, v239
	v_pk_mul_f32 v[20:21], v[20:21], v[152:153]
	v_pk_mul_f32 v[22:23], v[22:23], v[154:155]
	v_pk_mul_f32 v[16:17], v[16:17], v[156:157]
	v_pk_mul_f32 v[18:19], v[18:19], v[158:159]
	v_lshlrev_b32_e32 v152, 16, v240
	v_and_b32_e32 v153, 0xffff0000, v240
	v_lshlrev_b32_e32 v154, 16, v241
	v_and_b32_e32 v155, 0xffff0000, v241
	v_lshlrev_b32_e32 v156, 16, v242
	v_and_b32_e32 v157, 0xffff0000, v242
	v_lshlrev_b32_e32 v158, 16, v243
	v_and_b32_e32 v159, 0xffff0000, v243
	v_pk_add_f32 v[20:21], v[20:21], v[152:153]
	v_pk_add_f32 v[22:23], v[22:23], v[154:155]
	v_pk_add_f32 v[16:17], v[16:17], v[156:157]
	v_pk_add_f32 v[18:19], v[18:19], v[158:159]
	v_cvt_pk_bf16_f32 v132, v20, v21
	v_cvt_pk_bf16_f32 v133, v22, v23
	v_cvt_pk_bf16_f32 v134, v16, v17
	v_cvt_pk_bf16_f32 v135, v18, v19
	global_store_dwordx4 v130, v[132:135], s[12:13] sc1
	v_add_u32_e32 v130, 0x2000, v130
	s_waitcnt vmcnt(8)
	v_lshlrev_b32_e32 v152, 16, v188
	v_and_b32_e32 v153, 0xffff0000, v188
	v_lshlrev_b32_e32 v154, 16, v189
	v_and_b32_e32 v155, 0xffff0000, v189
	v_lshlrev_b32_e32 v156, 16, v190
	v_and_b32_e32 v157, 0xffff0000, v190
	v_lshlrev_b32_e32 v158, 16, v191
	v_and_b32_e32 v159, 0xffff0000, v191
	v_pk_mul_f32 v[12:13], v[12:13], v[152:153]
	v_pk_mul_f32 v[14:15], v[14:15], v[154:155]
	v_pk_mul_f32 v[8:9], v[8:9], v[156:157]
	v_pk_mul_f32 v[10:11], v[10:11], v[158:159]
	v_lshlrev_b32_e32 v152, 16, v192
	v_and_b32_e32 v153, 0xffff0000, v192
	v_lshlrev_b32_e32 v154, 16, v193
	v_and_b32_e32 v155, 0xffff0000, v193
	v_lshlrev_b32_e32 v156, 16, v194
	v_and_b32_e32 v157, 0xffff0000, v194
	v_lshlrev_b32_e32 v158, 16, v195
	v_and_b32_e32 v159, 0xffff0000, v195
	v_pk_add_f32 v[12:13], v[12:13], v[152:153]
	v_pk_add_f32 v[14:15], v[14:15], v[154:155]
	v_pk_add_f32 v[8:9], v[8:9], v[156:157]
	v_pk_add_f32 v[10:11], v[10:11], v[158:159]
	v_cvt_pk_bf16_f32 v132, v12, v13
	v_cvt_pk_bf16_f32 v133, v14, v15
	v_cvt_pk_bf16_f32 v134, v8, v9
	v_cvt_pk_bf16_f32 v135, v10, v11
	global_store_dwordx4 v130, v[132:135], s[12:13] sc1
	v_add_u32_e32 v130, 0x2000, v130
	s_waitcnt vmcnt(6)
	v_lshlrev_b32_e32 v152, 16, v196
	v_and_b32_e32 v153, 0xffff0000, v196
	v_lshlrev_b32_e32 v154, 16, v197
	v_and_b32_e32 v155, 0xffff0000, v197
	v_lshlrev_b32_e32 v156, 16, v198
	v_and_b32_e32 v157, 0xffff0000, v198
	v_lshlrev_b32_e32 v158, 16, v199
	v_and_b32_e32 v159, 0xffff0000, v199
	v_pk_mul_f32 v[4:5], v[4:5], v[152:153]
	v_pk_mul_f32 v[6:7], v[6:7], v[154:155]
	v_pk_mul_f32 v[0:1], v[0:1], v[156:157]
	v_pk_mul_f32 v[2:3], v[2:3], v[158:159]
	v_lshlrev_b32_e32 v152, 16, v200
	v_and_b32_e32 v153, 0xffff0000, v200
	v_lshlrev_b32_e32 v154, 16, v201
	v_and_b32_e32 v155, 0xffff0000, v201
	v_lshlrev_b32_e32 v156, 16, v202
	v_and_b32_e32 v157, 0xffff0000, v202
	v_lshlrev_b32_e32 v158, 16, v203
	v_and_b32_e32 v159, 0xffff0000, v203
	v_pk_add_f32 v[4:5], v[4:5], v[152:153]
	v_pk_add_f32 v[6:7], v[6:7], v[154:155]
	v_pk_add_f32 v[0:1], v[0:1], v[156:157]
	v_pk_add_f32 v[2:3], v[2:3], v[158:159]
	v_cvt_pk_bf16_f32 v132, v4, v5
	v_cvt_pk_bf16_f32 v133, v6, v7
	v_cvt_pk_bf16_f32 v134, v0, v1
	v_cvt_pk_bf16_f32 v135, v2, v3
	global_store_dwordx4 v130, v[132:135], s[12:13] sc1
	s_branch .LBB0_562
; __device__ __forceinline__ unsigned cvt_pk_bf16(float lo, float hi) { unsigned r; asm("v_cvt_pk_bf16_f32 %0, %1, %2" : "=v"(r) : "v"(lo), "v"(hi)); return r; }
; __device__ __forceinline__ float lo_bf(unsigned u) { return __uint_as_float(u << 16); }
; __device__ __forceinline__ float hi_bf(unsigned u) { return __uint_as_float(u & 0xffff0000u); }
;     __device__ __forceinline__ void operator()(f32x4 (&acc)[2][2][4][2], const GUnit& u, int wr, int wc, int fr, int fq, int tid) const {
;     ...
;                     for (int m = 0; m < 4; ++m) {
;                         const u32x4 g = ld_coh16(gp);
;                         u32x4 q = {0u, 0u, 0u, 0u}; if (sub != 1) q = ld_coh16(mp);
;                         f32x4 g0 = {lo_bf(g.x), hi_bf(g.x), lo_bf(g.y), hi_bf(g.y)}, g1 = {lo_bf(g.z), hi_bf(g.z), lo_bf(g.w), hi_bf(g.w)};
;                         f32x4 v0 = g0 * acc[ai][bj][m][0], v1 = g1 * acc[ai][bj][m][1];
;                         if (sub != 1) { v0 += (f32x4){lo_bf(q.x), hi_bf(q.x), lo_bf(q.y), hi_bf(q.y)}; v1 += (f32x4){lo_bf(q.z), hi_bf(q.z), lo_bf(q.w), hi_bf(q.w)}; }
;                         if (sub != 5) { u32x4 w; w.x = cvt_pk_bf16(v0[0], v0[1]); w.y = cvt_pk_bf16(v0[2], v0[3]); w.z = cvt_pk_bf16(v1[0], v1[1]); w.w = cvt_pk_bf16(v1[2], v1[3]); st_coh16(mp, w); }
;                         else { u32x4 w; w.x = cvt_pk_bf16(v0[0], v0[1]); w.y = cvt_pk_bf16(v0[2], v0[3]); w.z = cvt_pk_bf16(v1[0], v1[1]); w.w = cvt_pk_bf16(v1[2], v1[3]);
;                             *(u32x4*)(op + (size_t)(ai * HALF + m * 16) * DM + bj * HALF) = w; }
;                         gp += 4096; mp += 4096; asm volatile("" : "+v"(gp), "+v"(mp) :: "memory"); }
.Lbe_sub1:
	global_load_dwordx4 v[188:191], v129, s[22:23] sc1
	v_add_u32_e32 v129, 0x2000, v129
	global_load_dwordx4 v[196:199], v129, s[22:23] sc1
	v_add_u32_e32 v129, 0x2000, v129
	global_load_dwordx4 v[204:207], v129, s[22:23] sc1
	v_add_u32_e32 v129, 0x2000, v129
	global_load_dwordx4 v[212:215], v129, s[22:23] sc1
	v_add_u32_e32 v129, 0x2000, v129
	global_load_dwordx4 v[220:223], v129, s[22:23] sc1
	v_add_u32_e32 v129, 0x2000, v129
	global_load_dwordx4 v[228:231], v129, s[22:23] sc1
	v_add_u32_e32 v129, 0x2000, v129
	global_load_dwordx4 v[236:239], v129, s[22:23] sc1
	v_add_u32_e32 v129, 0x2000, v129
	s_waitcnt vmcnt(6)
	v_lshlrev_b32_e32 v152, 16, v188
	v_and_b32_e32 v153, 0xffff0000, v188
	v_lshlrev_b32_e32 v154, 16, v189
	v_and_b32_e32 v155, 0xffff0000, v189
	v_lshlrev_b32_e32 v156, 16, v190
	v_and_b32_e32 v157, 0xffff0000, v190
	v_lshlrev_b32_e32 v158, 16, v191
	v_and_b32_e32 v159, 0xffff0000, v191
	v_pk_mul_f32 v[124:125], v[124:125], v[152:153]
	v_pk_mul_f32 v[126:127], v[126:127], v[154:155]
	v_pk_mul_f32 v[120:121], v[120:121], v[156:157]
	v_pk_mul_f32 v[122:123], v[122:123], v[158:159]
	v_cvt_pk_bf16_f32 v132, v124, v125
	v_cvt_pk_bf16_f32 v133, v126, v127
	v_cvt_pk_bf16_f32 v134, v120, v121
	v_cvt_pk_bf16_f32 v135, v122, v123
	global_store_dwordx4 v130, v[132:135], s[12:13] sc1
	v_add_u32_e32 v130, 0x2000, v130
	global_load_dwordx4 v[188:191], v129, s[22:23] sc1
	v_add_u32_e32 v129, 0x2000, v129
	s_waitcnt vmcnt(7)
	v_lshlrev_b32_e32 v152, 16, v196
	v_and_b32_e32 v153, 0xffff0000, v196
	v_lshlrev_b32_e32 v154, 16, v197
	v_and_b32_e32 v155, 0xffff0000, v197
	v_lshlrev_b32_e32 v156, 16, v198
	v_and_b32_e32 v157, 0xffff0000, v198
	v_lshlrev_b32_e32 v158, 16, v199
	v_and_b32_e32 v159, 0xffff0000, v199
	v_pk_mul_f32 v[116:117], v[116:117], v[152:153]
	v_pk_mul_f32 v[118:119], v[118:119], v[154:155]
	v_pk_mul_f32 v[112:113], v[112:113], v[156:157]
	v_pk_mul_f32 v[114:115], v[114:115], v[158:159]
	v_cvt_pk_bf16_f32 v132, v116, v117
	v_cvt_pk_bf16_f32 v133, v118, v119
	v_cvt_pk_bf16_f32 v134, v112, v113
	v_cvt_pk_bf16_f32 v135, v114, v115
	global_store_dwordx4 v130, v[132:135], s[12:13] sc1
	v_add_u32_e32 v130, 0x2000, v130
	global_load_dwordx4 v[196:199], v129, s[22:23] sc1
	v_add_u32_e32 v129, 0x2000, v129
	s_waitcnt vmcnt(8)
	v_lshlrev_b32_e32 v152, 16, v204
	v_and_b32_e32 v153, 0xffff0000, v204
	v_lshlrev_b32_e32 v154, 16, v205
	v_and_b32_e32 v155, 0xffff0000, v205
	v_lshlrev_b32_e32 v156, 16, v206
	v_and_b32_e32 v157, 0xffff0000, v206
	v_lshlrev_b32_e32 v158, 16, v207
	v_and_b32_e32 v159, 0xffff0000, v207
	v_pk_mul_f32 v[108:109], v[108:109], v[152:153]
	v_pk_mul_f32 v[110:111], v[110:111], v[154:155]
	v_pk_mul_f32 v[104:105], v[104:105], v[156:157]
	v_pk_mul_f32 v[106:107], v[106:107], v[158:159]
	v_cvt_pk_bf16_f32 v132, v108, v109
	v_cvt_pk_bf16_f32 v133, v110, v111
	v_cvt_pk_bf16_f32 v134, v104, v105
	v_cvt_pk_bf16_f32 v135, v106, v107
	global_store_dwordx4 v130, v[132:135], s[12:13] sc1
	v_add_u32_e32 v130, 0x2000, v130
	global_load_dwordx4 v[204:207], v129, s[22:23] sc1
	v_add_u32_e32 v129, 0x2000, v129
	s_waitcnt vmcnt(9)
	v_lshlrev_b32_e32 v152, 16, v212
	v_and_b32_e32 v153, 0xffff0000, v212
	v_lshlrev_b32_e32 v154, 16, v213
	v_and_b32_e32 v155, 0xffff0000, v213
	v_lshlrev_b32_e32 v156, 16, v214
	v_and_b32_e32 v157, 0xffff0000, v214
	v_lshlrev_b32_e32 v158, 16, v215
	v_and_b32_e32 v159, 0xffff0000, v215
	v_pk_mul_f32 v[100:101], v[100:101], v[152:153]
	v_pk_mul_f32 v[102:103], v[102:103], v[154:155]
	v_pk_mul_f32 v[96:97], v[96:97], v[156:157]
	v_pk_mul_f32 v[98:99], v[98:99], v[158:159]
	v_cvt_pk_bf16_f32 v132, v100, v101
	v_cvt_pk_bf16_f32 v133, v102, v103
	v_cvt_pk_bf16_f32 v134, v96, v97
	v_cvt_pk_bf16_f32 v135, v98, v99
	global_store_dwordx4 v130, v[132:135], s[12:13] sc1
	v_add_u32_e32 v130, 0x2000, v130
	global_load_dwordx4 v[212:215], v129, s[22:23] sc1
	v_add_u32_e32 v129, 0x2000, v129
	s_waitcnt vmcnt(10)
	v_lshlrev_b32_e32 v152, 16, v220
	v_and_b32_e32 v153, 0xffff0000, v220
	v_lshlrev_b32_e32 v154, 16, v221
	v_and_b32_e32 v155, 0xffff0000, v221
	v_lshlrev_b32_e32 v156, 16, v222
	v_and_b32_e32 v157, 0xffff0000, v222
	v_lshlrev_b32_e32 v158, 16, v223
	v_and_b32_e32 v159, 0xffff0000, v223
	v_pk_mul_f32 v[92:93], v[92:93], v[152:153]
	v_pk_mul_f32 v[94:95], v[94:95], v[154:155]
	v_pk_mul_f32 v[88:89], v[88:89], v[156:157]
	v_pk_mul_f32 v[90:91], v[90:91], v[158:159]
	v_cvt_pk_bf16_f32 v132, v92, v93
	v_cvt_pk_bf16_f32 v133, v94, v95
	v_cvt_pk_bf16_f32 v134, v88, v89
	v_cvt_pk_bf16_f32 v135, v90, v91
	global_store_dwordx4 v130, v[132:135], s[12:13] sc1
	v_add_u32_e32 v130, 0x2000, v130
	global_load_dwordx4 v[220:223], v129, s[22:23] sc1
	v_add_u32_e32 v129, 0x2000, v129
	s_waitcnt vmcnt(11)
	v_lshlrev_b32_e32 v152, 16, v228
	v_and_b32_e32 v153, 0xffff0000, v228
	v_lshlrev_b32_e32 v154, 16, v229
	v_and_b32_e32 v155, 0xffff0000, v229
	v_lshlrev_b32_e32 v156, 16, v230
	v_and_b32_e32 v157, 0xffff0000, v230
	v_lshlrev_b32_e32 v158, 16, v231
	v_and_b32_e32 v159, 0xffff0000, v231
	v_pk_mul_f32 v[84:85], v[84:85], v[152:153]
	v_pk_mul_f32 v[86:87], v[86:87], v[154:155]
	v_pk_mul_f32 v[80:81], v[80:81], v[156:157]
	v_pk_mul_f32 v[82:83], v[82:83], v[158:159]
	v_cvt_pk_bf16_f32 v132, v84, v85
	v_cvt_pk_bf16_f32 v133, v86, v87
	v_cvt_pk_bf16_f32 v134, v80, v81
	v_cvt_pk_bf16_f32 v135, v82, v83
	global_store_dwordx4 v130, v[132:135], s[12:13] sc1
	v_add_u32_e32 v130, 0x2000, v130
	global_load_dwordx4 v[228:231], v129, s[22:23] sc1
	v_add_u32_e32 v129, 0x2000, v129
	s_waitcnt vmcnt(12)
; __device__ __forceinline__ unsigned cvt_pk_bf16(float lo, float hi) { unsigned r; asm("v_cvt_pk_bf16_f32 %0, %1, %2" : "=v"(r) : "v"(lo), "v"(hi)); return r; }
; __device__ __forceinline__ float lo_bf(unsigned u) { return __uint_as_float(u << 16); }
; __device__ __forceinline__ float hi_bf(unsigned u) { return __uint_as_float(u & 0xffff0000u); }
;     __device__ __forceinline__ void operator()(f32x4 (&acc)[2][2][4][2], const GUnit& u, int wr, int wc, int fr, int fq, int tid) const {
;     ...
;                     for (int m = 0; m < 4; ++m) {
;                         const u32x4 g = ld_coh16(gp);
;                         u32x4 q = {0u, 0u, 0u, 0u}; if (sub != 1) q = ld_coh16(mp);
;                         f32x4 g0 = {lo_bf(g.x), hi_bf(g.x), lo_bf(g.y), hi_bf(g.y)}, g1 = {lo_bf(g.z), hi_bf(g.z), lo_bf(g.w), hi_bf(g.w)};
;                         f32x4 v0 = g0 * acc[ai][bj][m][0], v1 = g1 * acc[ai][bj][m][1];
;                         if (sub != 1) { v0 += (f32x4){lo_bf(q.x), hi_bf(q.x), lo_bf(q.y), hi_bf(q.y)}; v1 += (f32x4){lo_bf(q.z), hi_bf(q.z), lo_bf(q.w), hi_bf(q.w)}; }
;                         if (sub != 5) { u32x4 w; w.x = cvt_pk_bf16(v0[0], v0[1]); w.y = cvt_pk_bf16(v0[2], v0[3]); w.z = cvt_pk_bf16(v1[0], v1[1]); w.w = cvt_pk_bf16(v1[2], v1[3]); st_coh16(mp, w); }
;                         else { u32x4 w; w.x = cvt_pk_bf16(v0[0], v0[1]); w.y = cvt_pk_bf16(v0[2], v0[3]); w.z = cvt_pk_bf16(v1[0], v1[1]); w.w = cvt_pk_bf16(v1[2], v1[3]);
;                             *(u32x4*)(op + (size_t)(ai * HALF + m * 16) * DM + bj * HALF) = w; }
;                         gp += 4096; mp += 4096; asm volatile("" : "+v"(gp), "+v"(mp) :: "memory"); }
	v_lshlrev_b32_e32 v152, 16, v236
	v_and_b32_e32 v153, 0xffff0000, v236
	v_lshlrev_b32_e32 v154, 16, v237
	v_and_b32_e32 v155, 0xffff0000, v237
	v_lshlrev_b32_e32 v156, 16, v238
	v_and_b32_e32 v157, 0xffff0000, v238
	v_lshlrev_b32_e32 v158, 16, v239
	v_and_b32_e32 v159, 0xffff0000, v239
	v_pk_mul_f32 v[76:77], v[76:77], v[152:153]
	v_pk_mul_f32 v[78:79], v[78:79], v[154:155]
	v_pk_mul_f32 v[72:73], v[72:73], v[156:157]
	v_pk_mul_f32 v[74:75], v[74:75], v[158:159]
	v_cvt_pk_bf16_f32 v132, v76, v77
	v_cvt_pk_bf16_f32 v133, v78, v79
	v_cvt_pk_bf16_f32 v134, v72, v73
	v_cvt_pk_bf16_f32 v135, v74, v75
	global_store_dwordx4 v130, v[132:135], s[12:13] sc1
	v_add_u32_e32 v130, 0x2000, v130
	global_load_dwordx4 v[236:239], v129, s[22:23] sc1
	v_add_u32_e32 v129, 0x2000, v129
	s_waitcnt vmcnt(12)
	v_lshlrev_b32_e32 v152, 16, v188
	v_and_b32_e32 v153, 0xffff0000, v188
	v_lshlrev_b32_e32 v154, 16, v189
	v_and_b32_e32 v155, 0xffff0000, v189
	v_lshlrev_b32_e32 v156, 16, v190
	v_and_b32_e32 v157, 0xffff0000, v190
	v_lshlrev_b32_e32 v158, 16, v191
	v_and_b32_e32 v159, 0xffff0000, v191
	v_pk_mul_f32 v[68:69], v[68:69], v[152:153]
	v_pk_mul_f32 v[70:71], v[70:71], v[154:155]
	v_pk_mul_f32 v[64:65], v[64:65], v[156:157]
	v_pk_mul_f32 v[66:67], v[66:67], v[158:159]
	v_cvt_pk_bf16_f32 v132, v68, v69
	v_cvt_pk_bf16_f32 v133, v70, v71
	v_cvt_pk_bf16_f32 v134, v64, v65
	v_cvt_pk_bf16_f32 v135, v66, v67
	global_store_dwordx4 v130, v[132:135], s[12:13] sc1
	v_add_u32_e32 v130, 0x2000, v130
	global_load_dwordx4 v[188:191], v129, s[22:23] sc1
	v_add_u32_e32 v129, 0x2000, v129
	s_waitcnt vmcnt(12)
	v_lshlrev_b32_e32 v152, 16, v196
	v_and_b32_e32 v153, 0xffff0000, v196
	v_lshlrev_b32_e32 v154, 16, v197
	v_and_b32_e32 v155, 0xffff0000, v197
	v_lshlrev_b32_e32 v156, 16, v198
	v_and_b32_e32 v157, 0xffff0000, v198
	v_lshlrev_b32_e32 v158, 16, v199
	v_and_b32_e32 v159, 0xffff0000, v199
	v_pk_mul_f32 v[60:61], v[60:61], v[152:153]
	v_pk_mul_f32 v[62:63], v[62:63], v[154:155]
	v_pk_mul_f32 v[56:57], v[56:57], v[156:157]
	v_pk_mul_f32 v[58:59], v[58:59], v[158:159]
	v_cvt_pk_bf16_f32 v132, v60, v61
	v_cvt_pk_bf16_f32 v133, v62, v63
	v_cvt_pk_bf16_f32 v134, v56, v57
	v_cvt_pk_bf16_f32 v135, v58, v59
	global_store_dwordx4 v130, v[132:135], s[12:13] sc1
	v_add_u32_e32 v130, 0x2000, v130
	global_load_dwordx4 v[196:199], v129, s[22:23] sc1
	v_add_u32_e32 v129, 0x2000, v129
	s_waitcnt vmcnt(12)
	v_lshlrev_b32_e32 v152, 16, v204
	v_and_b32_e32 v153, 0xffff0000, v204
	v_lshlrev_b32_e32 v154, 16, v205
	v_and_b32_e32 v155, 0xffff0000, v205
	v_lshlrev_b32_e32 v156, 16, v206
	v_and_b32_e32 v157, 0xffff0000, v206
	v_lshlrev_b32_e32 v158, 16, v207
	v_and_b32_e32 v159, 0xffff0000, v207
	v_pk_mul_f32 v[52:53], v[52:53], v[152:153]
	v_pk_mul_f32 v[54:55], v[54:55], v[154:155]
	v_pk_mul_f32 v[48:49], v[48:49], v[156:157]
	v_pk_mul_f32 v[50:51], v[50:51], v[158:159]
	v_cvt_pk_bf16_f32 v132, v52, v53
	v_cvt_pk_bf16_f32 v133, v54, v55
	v_cvt_pk_bf16_f32 v134, v48, v49
	v_cvt_pk_bf16_f32 v135, v50, v51
	global_store_dwordx4 v130, v[132:135], s[12:13] sc1
	v_add_u32_e32 v130, 0x2000, v130
	s_waitcnt vmcnt(11)
	v_lshlrev_b32_e32 v152, 16, v212
	v_and_b32_e32 v153, 0xffff0000, v212
	v_lshlrev_b32_e32 v154, 16, v213
	v_and_b32_e32 v155, 0xffff0000, v213
	v_lshlrev_b32_e32 v156, 16, v214
	v_and_b32_e32 v157, 0xffff0000, v214
	v_lshlrev_b32_e32 v158, 16, v215
	v_and_b32_e32 v159, 0xffff0000, v215
	v_pk_mul_f32 v[44:45], v[44:45], v[152:153]
	v_pk_mul_f32 v[46:47], v[46:47], v[154:155]
	v_pk_mul_f32 v[40:41], v[40:41], v[156:157]
	v_pk_mul_f32 v[42:43], v[42:43], v[158:159]
	v_cvt_pk_bf16_f32 v132, v44, v45
	v_cvt_pk_bf16_f32 v133, v46, v47
	v_cvt_pk_bf16_f32 v134, v40, v41
	v_cvt_pk_bf16_f32 v135, v42, v43
	global_store_dwordx4 v130, v[132:135], s[12:13] sc1
	v_add_u32_e32 v130, 0x2000, v130
	s_waitcnt vmcnt(10)
	v_lshlrev_b32_e32 v152, 16, v220
	v_and_b32_e32 v153, 0xffff0000, v220
	v_lshlrev_b32_e32 v154, 16, v221
	v_and_b32_e32 v155, 0xffff0000, v221
	v_lshlrev_b32_e32 v156, 16, v222
	v_and_b32_e32 v157, 0xffff0000, v222
	v_lshlrev_b32_e32 v158, 16, v223
	v_and_b32_e32 v159, 0xffff0000, v223
	v_pk_mul_f32 v[36:37], v[36:37], v[152:153]
	v_pk_mul_f32 v[38:39], v[38:39], v[154:155]
	v_pk_mul_f32 v[32:33], v[32:33], v[156:157]
	v_pk_mul_f32 v[34:35], v[34:35], v[158:159]
	v_cvt_pk_bf16_f32 v132, v36, v37
	v_cvt_pk_bf16_f32 v133, v38, v39
	v_cvt_pk_bf16_f32 v134, v32, v33
	v_cvt_pk_bf16_f32 v135, v34, v35
	global_store_dwordx4 v130, v[132:135], s[12:13] sc1
	v_add_u32_e32 v130, 0x2000, v130
	s_waitcnt vmcnt(9)
	v_lshlrev_b32_e32 v152, 16, v228
	v_and_b32_e32 v153, 0xffff0000, v228
	v_lshlrev_b32_e32 v154, 16, v229
	v_and_b32_e32 v155, 0xffff0000, v229
	v_lshlrev_b32_e32 v156, 16, v230
	v_and_b32_e32 v157, 0xffff0000, v230
	v_lshlrev_b32_e32 v158, 16, v231
	v_and_b32_e32 v159, 0xffff0000, v231
	v_pk_mul_f32 v[28:29], v[28:29], v[152:153]
	v_pk_mul_f32 v[30:31], v[30:31], v[154:155]
	v_pk_mul_f32 v[24:25], v[24:25], v[156:157]
	v_pk_mul_f32 v[26:27], v[26:27], v[158:159]
	v_cvt_pk_bf16_f32 v132, v28, v29
	v_cvt_pk_bf16_f32 v133, v30, v31
	v_cvt_pk_bf16_f32 v134, v24, v25
	v_cvt_pk_bf16_f32 v135, v26, v27
	global_store_dwordx4 v130, v[132:135], s[12:13] sc1
	v_add_u32_e32 v130, 0x2000, v130
	s_waitcnt vmcnt(8)
	v_lshlrev_b32_e32 v152, 16, v236
	v_and_b32_e32 v153, 0xffff0000, v236
	v_lshlrev_b32_e32 v154, 16, v237
	v_and_b32_e32 v155, 0xffff0000, v237
	v_lshlrev_b32_e32 v156, 16, v238
	v_and_b32_e32 v157, 0xffff0000, v238
	v_lshlrev_b32_e32 v158, 16, v239
	v_and_b32_e32 v159, 0xffff0000, v239
	v_pk_mul_f32 v[20:21], v[20:21], v[152:153]
	v_pk_mul_f32 v[22:23], v[22:23], v[154:155]
	v_pk_mul_f32 v[16:17], v[16:17], v[156:157]
	v_pk_mul_f32 v[18:19], v[18:19], v[158:159]
	v_cvt_pk_bf16_f32 v132, v20, v21
	v_cvt_pk_bf16_f32 v133, v22, v23
	v_cvt_pk_bf16_f32 v134, v16, v17
	v_cvt_pk_bf16_f32 v135, v18, v19
	global_store_dwordx4 v130, v[132:135], s[12:13] sc1
	v_add_u32_e32 v130, 0x2000, v130
	s_waitcnt vmcnt(7)
; __device__ __forceinline__ unsigned cvt_pk_bf16(float lo, float hi) { unsigned r; asm("v_cvt_pk_bf16_f32 %0, %1, %2" : "=v"(r) : "v"(lo), "v"(hi)); return r; }
; __device__ __forceinline__ float lo_bf(unsigned u) { return __uint_as_float(u << 16); }
; __device__ __forceinline__ float hi_bf(unsigned u) { return __uint_as_float(u & 0xffff0000u); }
;     __device__ __forceinline__ void operator()(f32x4 (&acc)[2][2][4][2], const GUnit& u, int wr, int wc, int fr, int fq, int tid) const {
;     ...
;                     for (int m = 0; m < 4; ++m) {
;                         const u32x4 g = ld_coh16(gp);
;                         u32x4 q = {0u, 0u, 0u, 0u}; if (sub != 1) q = ld_coh16(mp);
;                         f32x4 g0 = {lo_bf(g.x), hi_bf(g.x), lo_bf(g.y), hi_bf(g.y)}, g1 = {lo_bf(g.z), hi_bf(g.z), lo_bf(g.w), hi_bf(g.w)};
;                         f32x4 v0 = g0 * acc[ai][bj][m][0], v1 = g1 * acc[ai][bj][m][1];
;                         if (sub != 1) { v0 += (f32x4){lo_bf(q.x), hi_bf(q.x), lo_bf(q.y), hi_bf(q.y)}; v1 += (f32x4){lo_bf(q.z), hi_bf(q.z), lo_bf(q.w), hi_bf(q.w)}; }
;                         if (sub != 5) { u32x4 w; w.x = cvt_pk_bf16(v0[0], v0[1]); w.y = cvt_pk_bf16(v0[2], v0[3]); w.z = cvt_pk_bf16(v1[0], v1[1]); w.w = cvt_pk_bf16(v1[2], v1[3]); st_coh16(mp, w); }
;                         else { u32x4 w; w.x = cvt_pk_bf16(v0[0], v0[1]); w.y = cvt_pk_bf16(v0[2], v0[3]); w.z = cvt_pk_bf16(v1[0], v1[1]); w.w = cvt_pk_bf16(v1[2], v1[3]);
;                             *(u32x4*)(op + (size_t)(ai * HALF + m * 16) * DM + bj * HALF) = w; }
;                         gp += 4096; mp += 4096; asm volatile("" : "+v"(gp), "+v"(mp) :: "memory"); }
	v_lshlrev_b32_e32 v152, 16, v188
	v_and_b32_e32 v153, 0xffff0000, v188
	v_lshlrev_b32_e32 v154, 16, v189
	v_and_b32_e32 v155, 0xffff0000, v189
	v_lshlrev_b32_e32 v156, 16, v190
	v_and_b32_e32 v157, 0xffff0000, v190
	v_lshlrev_b32_e32 v158, 16, v191
	v_and_b32_e32 v159, 0xffff0000, v191
	v_pk_mul_f32 v[12:13], v[12:13], v[152:153]
	v_pk_mul_f32 v[14:15], v[14:15], v[154:155]
	v_pk_mul_f32 v[8:9], v[8:9], v[156:157]
	v_pk_mul_f32 v[10:11], v[10:11], v[158:159]
	v_cvt_pk_bf16_f32 v132, v12, v13
	v_cvt_pk_bf16_f32 v133, v14, v15
	v_cvt_pk_bf16_f32 v134, v8, v9
	v_cvt_pk_bf16_f32 v135, v10, v11
	global_store_dwordx4 v130, v[132:135], s[12:13] sc1
	v_add_u32_e32 v130, 0x2000, v130
	s_waitcnt vmcnt(6)
	v_lshlrev_b32_e32 v152, 16, v196
	v_and_b32_e32 v153, 0xffff0000, v196
	v_lshlrev_b32_e32 v154, 16, v197
	v_and_b32_e32 v155, 0xffff0000, v197
	v_lshlrev_b32_e32 v156, 16, v198
	v_and_b32_e32 v157, 0xffff0000, v198
	v_lshlrev_b32_e32 v158, 16, v199
	v_and_b32_e32 v159, 0xffff0000, v199
	v_pk_mul_f32 v[4:5], v[4:5], v[152:153]
	v_pk_mul_f32 v[6:7], v[6:7], v[154:155]
	v_pk_mul_f32 v[0:1], v[0:1], v[156:157]
	v_pk_mul_f32 v[2:3], v[2:3], v[158:159]
	v_cvt_pk_bf16_f32 v132, v4, v5
	v_cvt_pk_bf16_f32 v133, v6, v7
	v_cvt_pk_bf16_f32 v134, v0, v1
	v_cvt_pk_bf16_f32 v135, v2, v3
	global_store_dwordx4 v130, v[132:135], s[12:13] sc1
	s_branch .LBB0_562
.Lbe_sub5:
	global_load_dwordx4 v[188:191], v129, s[22:23] sc1
	global_load_dwordx4 v[192:195], v129, s[12:13] sc1
	v_add_u32_e32 v129, 0x2000, v129
	global_load_dwordx4 v[196:199], v129, s[22:23] sc1
	global_load_dwordx4 v[200:203], v129, s[12:13] sc1
	v_add_u32_e32 v129, 0x2000, v129
	global_load_dwordx4 v[204:207], v129, s[22:23] sc1
	global_load_dwordx4 v[208:211], v129, s[12:13] sc1
	v_add_u32_e32 v129, 0x2000, v129
	global_load_dwordx4 v[212:215], v129, s[22:23] sc1
	global_load_dwordx4 v[216:219], v129, s[12:13] sc1
	v_add_u32_e32 v129, 0x2000, v129
	global_load_dwordx4 v[220:223], v129, s[22:23] sc1
	global_load_dwordx4 v[224:227], v129, s[12:13] sc1
	v_add_u32_e32 v129, 0x2000, v129
	global_load_dwordx4 v[228:231], v129, s[22:23] sc1
	global_load_dwordx4 v[232:235], v129, s[12:13] sc1
	v_add_u32_e32 v129, 0x2000, v129
	global_load_dwordx4 v[236:239], v129, s[22:23] sc1
	global_load_dwordx4 v[240:243], v129, s[12:13] sc1
	v_add_u32_e32 v129, 0x2000, v129
	s_waitcnt vmcnt(12)
	v_lshlrev_b32_e32 v152, 16, v188
	v_and_b32_e32 v153, 0xffff0000, v188
	v_lshlrev_b32_e32 v154, 16, v189
	v_and_b32_e32 v155, 0xffff0000, v189
	v_lshlrev_b32_e32 v156, 16, v190
	v_and_b32_e32 v157, 0xffff0000, v190
	v_lshlrev_b32_e32 v158, 16, v191
	v_and_b32_e32 v159, 0xffff0000, v191
	v_pk_mul_f32 v[124:125], v[124:125], v[152:153]
	v_pk_mul_f32 v[126:127], v[126:127], v[154:155]
	v_pk_mul_f32 v[120:121], v[120:121], v[156:157]
	v_pk_mul_f32 v[122:123], v[122:123], v[158:159]
	v_lshlrev_b32_e32 v152, 16, v192
	v_and_b32_e32 v153, 0xffff0000, v192
	v_lshlrev_b32_e32 v154, 16, v193
	v_and_b32_e32 v155, 0xffff0000, v193
	v_lshlrev_b32_e32 v156, 16, v194
	v_and_b32_e32 v157, 0xffff0000, v194
	v_lshlrev_b32_e32 v158, 16, v195
	v_and_b32_e32 v159, 0xffff0000, v195
	v_pk_add_f32 v[124:125], v[124:125], v[152:153]
	v_pk_add_f32 v[126:127], v[126:127], v[154:155]
	v_pk_add_f32 v[120:121], v[120:121], v[156:157]
	v_pk_add_f32 v[122:123], v[122:123], v[158:159]
	v_cvt_pk_bf16_f32 v132, v124, v125
	v_cvt_pk_bf16_f32 v133, v126, v127
	v_cvt_pk_bf16_f32 v134, v120, v121
	v_cvt_pk_bf16_f32 v135, v122, v123
	global_store_dwordx4 v131, v[132:135], s[54:55]
	global_load_dwordx4 v[188:191], v129, s[22:23] sc1
	global_load_dwordx4 v[192:195], v129, s[12:13] sc1
	v_add_u32_e32 v129, 0x2000, v129
	s_waitcnt vmcnt(13)
	v_lshlrev_b32_e32 v152, 16, v196
	v_and_b32_e32 v153, 0xffff0000, v196
	v_lshlrev_b32_e32 v154, 16, v197
	v_and_b32_e32 v155, 0xffff0000, v197
	v_lshlrev_b32_e32 v156, 16, v198
	v_and_b32_e32 v157, 0xffff0000, v198
	v_lshlrev_b32_e32 v158, 16, v199
	v_and_b32_e32 v159, 0xffff0000, v199
	v_pk_mul_f32 v[116:117], v[116:117], v[152:153]
	v_pk_mul_f32 v[118:119], v[118:119], v[154:155]
	v_pk_mul_f32 v[112:113], v[112:113], v[156:157]
	v_pk_mul_f32 v[114:115], v[114:115], v[158:159]
	v_lshlrev_b32_e32 v152, 16, v200
	v_and_b32_e32 v153, 0xffff0000, v200
	v_lshlrev_b32_e32 v154, 16, v201
	v_and_b32_e32 v155, 0xffff0000, v201
	v_lshlrev_b32_e32 v156, 16, v202
	v_and_b32_e32 v157, 0xffff0000, v202
	v_lshlrev_b32_e32 v158, 16, v203
	v_and_b32_e32 v159, 0xffff0000, v203
	v_pk_add_f32 v[116:117], v[116:117], v[152:153]
	v_pk_add_f32 v[118:119], v[118:119], v[154:155]
	v_pk_add_f32 v[112:113], v[112:113], v[156:157]
	v_pk_add_f32 v[114:115], v[114:115], v[158:159]
	v_cvt_pk_bf16_f32 v132, v116, v117
	v_cvt_pk_bf16_f32 v133, v118, v119
	v_cvt_pk_bf16_f32 v134, v112, v113
	v_cvt_pk_bf16_f32 v135, v114, v115
	v_add_u32_e32 v138, 0x10000, v131
	global_store_dwordx4 v138, v[132:135], s[54:55]
	global_load_dwordx4 v[196:199], v129, s[22:23] sc1
	global_load_dwordx4 v[200:203], v129, s[12:13] sc1
	v_add_u32_e32 v129, 0x2000, v129
	s_waitcnt vmcnt(14)
; __device__ __forceinline__ unsigned cvt_pk_bf16(float lo, float hi) { unsigned r; asm("v_cvt_pk_bf16_f32 %0, %1, %2" : "=v"(r) : "v"(lo), "v"(hi)); return r; }
; __device__ __forceinline__ float lo_bf(unsigned u) { return __uint_as_float(u << 16); }
; __device__ __forceinline__ float hi_bf(unsigned u) { return __uint_as_float(u & 0xffff0000u); }
;     __device__ __forceinline__ void operator()(f32x4 (&acc)[2][2][4][2], const GUnit& u, int wr, int wc, int fr, int fq, int tid) const {
;     ...
;                     for (int m = 0; m < 4; ++m) {
;                         const u32x4 g = ld_coh16(gp);
;                         u32x4 q = {0u, 0u, 0u, 0u}; if (sub != 1) q = ld_coh16(mp);
;                         f32x4 g0 = {lo_bf(g.x), hi_bf(g.x), lo_bf(g.y), hi_bf(g.y)}, g1 = {lo_bf(g.z), hi_bf(g.z), lo_bf(g.w), hi_bf(g.w)};
;                         f32x4 v0 = g0 * acc[ai][bj][m][0], v1 = g1 * acc[ai][bj][m][1];
;                         if (sub != 1) { v0 += (f32x4){lo_bf(q.x), hi_bf(q.x), lo_bf(q.y), hi_bf(q.y)}; v1 += (f32x4){lo_bf(q.z), hi_bf(q.z), lo_bf(q.w), hi_bf(q.w)}; }
;                         if (sub != 5) { u32x4 w; w.x = cvt_pk_bf16(v0[0], v0[1]); w.y = cvt_pk_bf16(v0[2], v0[3]); w.z = cvt_pk_bf16(v1[0], v1[1]); w.w = cvt_pk_bf16(v1[2], v1[3]); st_coh16(mp, w); }
;                         else { u32x4 w; w.x = cvt_pk_bf16(v0[0], v0[1]); w.y = cvt_pk_bf16(v0[2], v0[3]); w.z = cvt_pk_bf16(v1[0], v1[1]); w.w = cvt_pk_bf16(v1[2], v1[3]);
;                             *(u32x4*)(op + (size_t)(ai * HALF + m * 16) * DM + bj * HALF) = w; }
;                         gp += 4096; mp += 4096; asm volatile("" : "+v"(gp), "+v"(mp) :: "memory"); }
	v_lshlrev_b32_e32 v152, 16, v204
	v_and_b32_e32 v153, 0xffff0000, v204
	v_lshlrev_b32_e32 v154, 16, v205
	v_and_b32_e32 v155, 0xffff0000, v205
	v_lshlrev_b32_e32 v156, 16, v206
	v_and_b32_e32 v157, 0xffff0000, v206
	v_lshlrev_b32_e32 v158, 16, v207
	v_and_b32_e32 v159, 0xffff0000, v207
	v_pk_mul_f32 v[108:109], v[108:109], v[152:153]
	v_pk_mul_f32 v[110:111], v[110:111], v[154:155]
	v_pk_mul_f32 v[104:105], v[104:105], v[156:157]
	v_pk_mul_f32 v[106:107], v[106:107], v[158:159]
	v_lshlrev_b32_e32 v152, 16, v208
	v_and_b32_e32 v153, 0xffff0000, v208
	v_lshlrev_b32_e32 v154, 16, v209
	v_and_b32_e32 v155, 0xffff0000, v209
	v_lshlrev_b32_e32 v156, 16, v210
	v_and_b32_e32 v157, 0xffff0000, v210
	v_lshlrev_b32_e32 v158, 16, v211
	v_and_b32_e32 v159, 0xffff0000, v211
	v_pk_add_f32 v[108:109], v[108:109], v[152:153]
	v_pk_add_f32 v[110:111], v[110:111], v[154:155]
	v_pk_add_f32 v[104:105], v[104:105], v[156:157]
	v_pk_add_f32 v[106:107], v[106:107], v[158:159]
	v_cvt_pk_bf16_f32 v132, v108, v109
	v_cvt_pk_bf16_f32 v133, v110, v111
	v_cvt_pk_bf16_f32 v134, v104, v105
	v_cvt_pk_bf16_f32 v135, v106, v107
	v_add_u32_e32 v138, 0x20000, v131
	global_store_dwordx4 v138, v[132:135], s[54:55]
	global_load_dwordx4 v[204:207], v129, s[22:23] sc1
	global_load_dwordx4 v[208:211], v129, s[12:13] sc1
	v_add_u32_e32 v129, 0x2000, v129
	s_waitcnt vmcnt(15)
	v_lshlrev_b32_e32 v152, 16, v212
	v_and_b32_e32 v153, 0xffff0000, v212
	v_lshlrev_b32_e32 v154, 16, v213
	v_and_b32_e32 v155, 0xffff0000, v213
	v_lshlrev_b32_e32 v156, 16, v214
	v_and_b32_e32 v157, 0xffff0000, v214
	v_lshlrev_b32_e32 v158, 16, v215
	v_and_b32_e32 v159, 0xffff0000, v215
	v_pk_mul_f32 v[100:101], v[100:101], v[152:153]
	v_pk_mul_f32 v[102:103], v[102:103], v[154:155]
	v_pk_mul_f32 v[96:97], v[96:97], v[156:157]
	v_pk_mul_f32 v[98:99], v[98:99], v[158:159]
	v_lshlrev_b32_e32 v152, 16, v216
	v_and_b32_e32 v153, 0xffff0000, v216
	v_lshlrev_b32_e32 v154, 16, v217
	v_and_b32_e32 v155, 0xffff0000, v217
	v_lshlrev_b32_e32 v156, 16, v218
	v_and_b32_e32 v157, 0xffff0000, v218
	v_lshlrev_b32_e32 v158, 16, v219
	v_and_b32_e32 v159, 0xffff0000, v219
	v_pk_add_f32 v[100:101], v[100:101], v[152:153]
	v_pk_add_f32 v[102:103], v[102:103], v[154:155]
	v_pk_add_f32 v[96:97], v[96:97], v[156:157]
	v_pk_add_f32 v[98:99], v[98:99], v[158:159]
	v_cvt_pk_bf16_f32 v132, v100, v101
	v_cvt_pk_bf16_f32 v133, v102, v103
	v_cvt_pk_bf16_f32 v134, v96, v97
	v_cvt_pk_bf16_f32 v135, v98, v99
	v_add_u32_e32 v138, 0x30000, v131
	global_store_dwordx4 v138, v[132:135], s[54:55]
	global_load_dwordx4 v[212:215], v129, s[22:23] sc1
	global_load_dwordx4 v[216:219], v129, s[12:13] sc1
	v_add_u32_e32 v129, 0x2000, v129
	s_waitcnt vmcnt(16)
	v_lshlrev_b32_e32 v152, 16, v220
	v_and_b32_e32 v153, 0xffff0000, v220
	v_lshlrev_b32_e32 v154, 16, v221
	v_and_b32_e32 v155, 0xffff0000, v221
	v_lshlrev_b32_e32 v156, 16, v222
	v_and_b32_e32 v157, 0xffff0000, v222
	v_lshlrev_b32_e32 v158, 16, v223
	v_and_b32_e32 v159, 0xffff0000, v223
	v_pk_mul_f32 v[92:93], v[92:93], v[152:153]
	v_pk_mul_f32 v[94:95], v[94:95], v[154:155]
	v_pk_mul_f32 v[88:89], v[88:89], v[156:157]
	v_pk_mul_f32 v[90:91], v[90:91], v[158:159]
	v_lshlrev_b32_e32 v152, 16, v224
	v_and_b32_e32 v153, 0xffff0000, v224
	v_lshlrev_b32_e32 v154, 16, v225
	v_and_b32_e32 v155, 0xffff0000, v225
	v_lshlrev_b32_e32 v156, 16, v226
	v_and_b32_e32 v157, 0xffff0000, v226
	v_lshlrev_b32_e32 v158, 16, v227
	v_and_b32_e32 v159, 0xffff0000, v227
	v_pk_add_f32 v[92:93], v[92:93], v[152:153]
	v_pk_add_f32 v[94:95], v[94:95], v[154:155]
	v_pk_add_f32 v[88:89], v[88:89], v[156:157]
	v_pk_add_f32 v[90:91], v[90:91], v[158:159]
	v_cvt_pk_bf16_f32 v132, v92, v93
	v_cvt_pk_bf16_f32 v133, v94, v95
	v_cvt_pk_bf16_f32 v134, v88, v89
	v_cvt_pk_bf16_f32 v135, v90, v91
	v_add_u32_e32 v138, 0x100, v131
	global_store_dwordx4 v138, v[132:135], s[54:55]
	global_load_dwordx4 v[220:223], v129, s[22:23] sc1
	global_load_dwordx4 v[224:227], v129, s[12:13] sc1
	v_add_u32_e32 v129, 0x2000, v129
	s_waitcnt vmcnt(17)
	v_lshlrev_b32_e32 v152, 16, v228
	v_and_b32_e32 v153, 0xffff0000, v228
	v_lshlrev_b32_e32 v154, 16, v229
	v_and_b32_e32 v155, 0xffff0000, v229
	v_lshlrev_b32_e32 v156, 16, v230
	v_and_b32_e32 v157, 0xffff0000, v230
	v_lshlrev_b32_e32 v158, 16, v231
	v_and_b32_e32 v159, 0xffff0000, v231
	v_pk_mul_f32 v[84:85], v[84:85], v[152:153]
	v_pk_mul_f32 v[86:87], v[86:87], v[154:155]
	v_pk_mul_f32 v[80:81], v[80:81], v[156:157]
	v_pk_mul_f32 v[82:83], v[82:83], v[158:159]
	v_lshlrev_b32_e32 v152, 16, v232
	v_and_b32_e32 v153, 0xffff0000, v232
	v_lshlrev_b32_e32 v154, 16, v233
	v_and_b32_e32 v155, 0xffff0000, v233
	v_lshlrev_b32_e32 v156, 16, v234
	v_and_b32_e32 v157, 0xffff0000, v234
	v_lshlrev_b32_e32 v158, 16, v235
	v_and_b32_e32 v159, 0xffff0000, v235
	v_pk_add_f32 v[84:85], v[84:85], v[152:153]
	v_pk_add_f32 v[86:87], v[86:87], v[154:155]
	v_pk_add_f32 v[80:81], v[80:81], v[156:157]
	v_pk_add_f32 v[82:83], v[82:83], v[158:159]
	v_cvt_pk_bf16_f32 v132, v84, v85
	v_cvt_pk_bf16_f32 v133, v86, v87
	v_cvt_pk_bf16_f32 v134, v80, v81
	v_cvt_pk_bf16_f32 v135, v82, v83
	v_add_u32_e32 v138, 0x10100, v131
	global_store_dwordx4 v138, v[132:135], s[54:55]
	global_load_dwordx4 v[228:231], v129, s[22:23] sc1
	global_load_dwordx4 v[232:235], v129, s[12:13] sc1
	v_add_u32_e32 v129, 0x2000, v129
	s_waitcnt vmcnt(18)
; __device__ __forceinline__ unsigned cvt_pk_bf16(float lo, float hi) { unsigned r; asm("v_cvt_pk_bf16_f32 %0, %1, %2" : "=v"(r) : "v"(lo), "v"(hi)); return r; }
; __device__ __forceinline__ float lo_bf(unsigned u) { return __uint_as_float(u << 16); }
; __device__ __forceinline__ float hi_bf(unsigned u) { return __uint_as_float(u & 0xffff0000u); }
;     __device__ __forceinline__ void operator()(f32x4 (&acc)[2][2][4][2], const GUnit& u, int wr, int wc, int fr, int fq, int tid) const {
;     ...
;                     for (int m = 0; m < 4; ++m) {
;                         const u32x4 g = ld_coh16(gp);
;                         u32x4 q = {0u, 0u, 0u, 0u}; if (sub != 1) q = ld_coh16(mp);
;                         f32x4 g0 = {lo_bf(g.x), hi_bf(g.x), lo_bf(g.y), hi_bf(g.y)}, g1 = {lo_bf(g.z), hi_bf(g.z), lo_bf(g.w), hi_bf(g.w)};
;                         f32x4 v0 = g0 * acc[ai][bj][m][0], v1 = g1 * acc[ai][bj][m][1];
;                         if (sub != 1) { v0 += (f32x4){lo_bf(q.x), hi_bf(q.x), lo_bf(q.y), hi_bf(q.y)}; v1 += (f32x4){lo_bf(q.z), hi_bf(q.z), lo_bf(q.w), hi_bf(q.w)}; }
;                         if (sub != 5) { u32x4 w; w.x = cvt_pk_bf16(v0[0], v0[1]); w.y = cvt_pk_bf16(v0[2], v0[3]); w.z = cvt_pk_bf16(v1[0], v1[1]); w.w = cvt_pk_bf16(v1[2], v1[3]); st_coh16(mp, w); }
;                         else { u32x4 w; w.x = cvt_pk_bf16(v0[0], v0[1]); w.y = cvt_pk_bf16(v0[2], v0[3]); w.z = cvt_pk_bf16(v1[0], v1[1]); w.w = cvt_pk_bf16(v1[2], v1[3]);
;                             *(u32x4*)(op + (size_t)(ai * HALF + m * 16) * DM + bj * HALF) = w; }
;                         gp += 4096; mp += 4096; asm volatile("" : "+v"(gp), "+v"(mp) :: "memory"); }
	v_lshlrev_b32_e32 v152, 16, v236
	v_and_b32_e32 v153, 0xffff0000, v236
	v_lshlrev_b32_e32 v154, 16, v237
	v_and_b32_e32 v155, 0xffff0000, v237
	v_lshlrev_b32_e32 v156, 16, v238
	v_and_b32_e32 v157, 0xffff0000, v238
	v_lshlrev_b32_e32 v158, 16, v239
	v_and_b32_e32 v159, 0xffff0000, v239
	v_pk_mul_f32 v[76:77], v[76:77], v[152:153]
	v_pk_mul_f32 v[78:79], v[78:79], v[154:155]
	v_pk_mul_f32 v[72:73], v[72:73], v[156:157]
	v_pk_mul_f32 v[74:75], v[74:75], v[158:159]
	v_lshlrev_b32_e32 v152, 16, v240
	v_and_b32_e32 v153, 0xffff0000, v240
	v_lshlrev_b32_e32 v154, 16, v241
	v_and_b32_e32 v155, 0xffff0000, v241
	v_lshlrev_b32_e32 v156, 16, v242
	v_and_b32_e32 v157, 0xffff0000, v242
	v_lshlrev_b32_e32 v158, 16, v243
	v_and_b32_e32 v159, 0xffff0000, v243
	v_pk_add_f32 v[76:77], v[76:77], v[152:153]
	v_pk_add_f32 v[78:79], v[78:79], v[154:155]
	v_pk_add_f32 v[72:73], v[72:73], v[156:157]
	v_pk_add_f32 v[74:75], v[74:75], v[158:159]
	v_cvt_pk_bf16_f32 v132, v76, v77
	v_cvt_pk_bf16_f32 v133, v78, v79
	v_cvt_pk_bf16_f32 v134, v72, v73
	v_cvt_pk_bf16_f32 v135, v74, v75
	v_add_u32_e32 v138, 0x20100, v131
	global_store_dwordx4 v138, v[132:135], s[54:55]
	global_load_dwordx4 v[236:239], v129, s[22:23] sc1
	global_load_dwordx4 v[240:243], v129, s[12:13] sc1
	v_add_u32_e32 v129, 0x2000, v129
	s_waitcnt vmcnt(18)
	v_lshlrev_b32_e32 v152, 16, v188
	v_and_b32_e32 v153, 0xffff0000, v188
	v_lshlrev_b32_e32 v154, 16, v189
	v_and_b32_e32 v155, 0xffff0000, v189
	v_lshlrev_b32_e32 v156, 16, v190
	v_and_b32_e32 v157, 0xffff0000, v190
	v_lshlrev_b32_e32 v158, 16, v191
	v_and_b32_e32 v159, 0xffff0000, v191
	v_pk_mul_f32 v[68:69], v[68:69], v[152:153]
	v_pk_mul_f32 v[70:71], v[70:71], v[154:155]
	v_pk_mul_f32 v[64:65], v[64:65], v[156:157]
	v_pk_mul_f32 v[66:67], v[66:67], v[158:159]
	v_lshlrev_b32_e32 v152, 16, v192
	v_and_b32_e32 v153, 0xffff0000, v192
	v_lshlrev_b32_e32 v154, 16, v193
	v_and_b32_e32 v155, 0xffff0000, v193
	v_lshlrev_b32_e32 v156, 16, v194
	v_and_b32_e32 v157, 0xffff0000, v194
	v_lshlrev_b32_e32 v158, 16, v195
	v_and_b32_e32 v159, 0xffff0000, v195
	v_pk_add_f32 v[68:69], v[68:69], v[152:153]
	v_pk_add_f32 v[70:71], v[70:71], v[154:155]
	v_pk_add_f32 v[64:65], v[64:65], v[156:157]
	v_pk_add_f32 v[66:67], v[66:67], v[158:159]
	v_cvt_pk_bf16_f32 v132, v68, v69
	v_cvt_pk_bf16_f32 v133, v70, v71
	v_cvt_pk_bf16_f32 v134, v64, v65
	v_cvt_pk_bf16_f32 v135, v66, v67
	v_add_u32_e32 v138, 0x30100, v131
	global_store_dwordx4 v138, v[132:135], s[54:55]
	global_load_dwordx4 v[188:191], v129, s[22:23] sc1
	global_load_dwordx4 v[192:195], v129, s[12:13] sc1
	v_add_u32_e32 v129, 0x2000, v129
	s_waitcnt vmcnt(18)
	v_lshlrev_b32_e32 v152, 16, v196
	v_and_b32_e32 v153, 0xffff0000, v196
	v_lshlrev_b32_e32 v154, 16, v197
	v_and_b32_e32 v155, 0xffff0000, v197
	v_lshlrev_b32_e32 v156, 16, v198
	v_and_b32_e32 v157, 0xffff0000, v198
	v_lshlrev_b32_e32 v158, 16, v199
	v_and_b32_e32 v159, 0xffff0000, v199
	v_pk_mul_f32 v[60:61], v[60:61], v[152:153]
	v_pk_mul_f32 v[62:63], v[62:63], v[154:155]
	v_pk_mul_f32 v[56:57], v[56:57], v[156:157]
	v_pk_mul_f32 v[58:59], v[58:59], v[158:159]
	v_lshlrev_b32_e32 v152, 16, v200
	v_and_b32_e32 v153, 0xffff0000, v200
	v_lshlrev_b32_e32 v154, 16, v201
	v_and_b32_e32 v155, 0xffff0000, v201
	v_lshlrev_b32_e32 v156, 16, v202
	v_and_b32_e32 v157, 0xffff0000, v202
	v_lshlrev_b32_e32 v158, 16, v203
	v_and_b32_e32 v159, 0xffff0000, v203
	v_pk_add_f32 v[60:61], v[60:61], v[152:153]
	v_pk_add_f32 v[62:63], v[62:63], v[154:155]
	v_pk_add_f32 v[56:57], v[56:57], v[156:157]
	v_pk_add_f32 v[58:59], v[58:59], v[158:159]
	v_cvt_pk_bf16_f32 v132, v60, v61
	v_cvt_pk_bf16_f32 v133, v62, v63
	v_cvt_pk_bf16_f32 v134, v56, v57
	v_cvt_pk_bf16_f32 v135, v58, v59
	v_add_u32_e32 v138, 0x80000, v131
	global_store_dwordx4 v138, v[132:135], s[54:55]
	global_load_dwordx4 v[196:199], v129, s[22:23] sc1
	global_load_dwordx4 v[200:203], v129, s[12:13] sc1
	v_add_u32_e32 v129, 0x2000, v129
	s_waitcnt vmcnt(18)
	v_lshlrev_b32_e32 v152, 16, v204
	v_and_b32_e32 v153, 0xffff0000, v204
	v_lshlrev_b32_e32 v154, 16, v205
	v_and_b32_e32 v155, 0xffff0000, v205
	v_lshlrev_b32_e32 v156, 16, v206
	v_and_b32_e32 v157, 0xffff0000, v206
	v_lshlrev_b32_e32 v158, 16, v207
	v_and_b32_e32 v159, 0xffff0000, v207
	v_pk_mul_f32 v[52:53], v[52:53], v[152:153]
	v_pk_mul_f32 v[54:55], v[54:55], v[154:155]
	v_pk_mul_f32 v[48:49], v[48:49], v[156:157]
	v_pk_mul_f32 v[50:51], v[50:51], v[158:159]
	v_lshlrev_b32_e32 v152, 16, v208
	v_and_b32_e32 v153, 0xffff0000, v208
	v_lshlrev_b32_e32 v154, 16, v209
	v_and_b32_e32 v155, 0xffff0000, v209
	v_lshlrev_b32_e32 v156, 16, v210
	v_and_b32_e32 v157, 0xffff0000, v210
	v_lshlrev_b32_e32 v158, 16, v211
	v_and_b32_e32 v159, 0xffff0000, v211
	v_pk_add_f32 v[52:53], v[52:53], v[152:153]
	v_pk_add_f32 v[54:55], v[54:55], v[154:155]
	v_pk_add_f32 v[48:49], v[48:49], v[156:157]
	v_pk_add_f32 v[50:51], v[50:51], v[158:159]
	v_cvt_pk_bf16_f32 v132, v52, v53
	v_cvt_pk_bf16_f32 v133, v54, v55
	v_cvt_pk_bf16_f32 v134, v48, v49
	v_cvt_pk_bf16_f32 v135, v50, v51
	v_add_u32_e32 v138, 0x90000, v131
	global_store_dwordx4 v138, v[132:135], s[54:55]
	s_waitcnt vmcnt(16)
; __device__ __forceinline__ unsigned cvt_pk_bf16(float lo, float hi) { unsigned r; asm("v_cvt_pk_bf16_f32 %0, %1, %2" : "=v"(r) : "v"(lo), "v"(hi)); return r; }
; __device__ __forceinline__ float lo_bf(unsigned u) { return __uint_as_float(u << 16); }
; __device__ __forceinline__ float hi_bf(unsigned u) { return __uint_as_float(u & 0xffff0000u); }
;     __device__ __forceinline__ void operator()(f32x4 (&acc)[2][2][4][2], const GUnit& u, int wr, int wc, int fr, int fq, int tid) const {
;     ...
;                     for (int m = 0; m < 4; ++m) {
;                         const u32x4 g = ld_coh16(gp);
;                         u32x4 q = {0u, 0u, 0u, 0u}; if (sub != 1) q = ld_coh16(mp);
;                         f32x4 g0 = {lo_bf(g.x), hi_bf(g.x), lo_bf(g.y), hi_bf(g.y)}, g1 = {lo_bf(g.z), hi_bf(g.z), lo_bf(g.w), hi_bf(g.w)};
;                         f32x4 v0 = g0 * acc[ai][bj][m][0], v1 = g1 * acc[ai][bj][m][1];
;                         if (sub != 1) { v0 += (f32x4){lo_bf(q.x), hi_bf(q.x), lo_bf(q.y), hi_bf(q.y)}; v1 += (f32x4){lo_bf(q.z), hi_bf(q.z), lo_bf(q.w), hi_bf(q.w)}; }
;                         if (sub != 5) { u32x4 w; w.x = cvt_pk_bf16(v0[0], v0[1]); w.y = cvt_pk_bf16(v0[2], v0[3]); w.z = cvt_pk_bf16(v1[0], v1[1]); w.w = cvt_pk_bf16(v1[2], v1[3]); st_coh16(mp, w); }
;                         else { u32x4 w; w.x = cvt_pk_bf16(v0[0], v0[1]); w.y = cvt_pk_bf16(v0[2], v0[3]); w.z = cvt_pk_bf16(v1[0], v1[1]); w.w = cvt_pk_bf16(v1[2], v1[3]);
;                             *(u32x4*)(op + (size_t)(ai * HALF + m * 16) * DM + bj * HALF) = w; }
;                         gp += 4096; mp += 4096; asm volatile("" : "+v"(gp), "+v"(mp) :: "memory"); }
	v_lshlrev_b32_e32 v152, 16, v212
	v_and_b32_e32 v153, 0xffff0000, v212
	v_lshlrev_b32_e32 v154, 16, v213
	v_and_b32_e32 v155, 0xffff0000, v213
	v_lshlrev_b32_e32 v156, 16, v214
	v_and_b32_e32 v157, 0xffff0000, v214
	v_lshlrev_b32_e32 v158, 16, v215
	v_and_b32_e32 v159, 0xffff0000, v215
	v_pk_mul_f32 v[44:45], v[44:45], v[152:153]
	v_pk_mul_f32 v[46:47], v[46:47], v[154:155]
	v_pk_mul_f32 v[40:41], v[40:41], v[156:157]
	v_pk_mul_f32 v[42:43], v[42:43], v[158:159]
	v_lshlrev_b32_e32 v152, 16, v216
	v_and_b32_e32 v153, 0xffff0000, v216
	v_lshlrev_b32_e32 v154, 16, v217
	v_and_b32_e32 v155, 0xffff0000, v217
	v_lshlrev_b32_e32 v156, 16, v218
	v_and_b32_e32 v157, 0xffff0000, v218
	v_lshlrev_b32_e32 v158, 16, v219
	v_and_b32_e32 v159, 0xffff0000, v219
	v_pk_add_f32 v[44:45], v[44:45], v[152:153]
	v_pk_add_f32 v[46:47], v[46:47], v[154:155]
	v_pk_add_f32 v[40:41], v[40:41], v[156:157]
	v_pk_add_f32 v[42:43], v[42:43], v[158:159]
	v_cvt_pk_bf16_f32 v132, v44, v45
	v_cvt_pk_bf16_f32 v133, v46, v47
	v_cvt_pk_bf16_f32 v134, v40, v41
	v_cvt_pk_bf16_f32 v135, v42, v43
	v_add_u32_e32 v138, 0xa0000, v131
	global_store_dwordx4 v138, v[132:135], s[54:55]
	s_waitcnt vmcnt(14)
	v_lshlrev_b32_e32 v152, 16, v220
	v_and_b32_e32 v153, 0xffff0000, v220
	v_lshlrev_b32_e32 v154, 16, v221
	v_and_b32_e32 v155, 0xffff0000, v221
	v_lshlrev_b32_e32 v156, 16, v222
	v_and_b32_e32 v157, 0xffff0000, v222
	v_lshlrev_b32_e32 v158, 16, v223
	v_and_b32_e32 v159, 0xffff0000, v223
	v_pk_mul_f32 v[36:37], v[36:37], v[152:153]
	v_pk_mul_f32 v[38:39], v[38:39], v[154:155]
	v_pk_mul_f32 v[32:33], v[32:33], v[156:157]
	v_pk_mul_f32 v[34:35], v[34:35], v[158:159]
	v_lshlrev_b32_e32 v152, 16, v224
	v_and_b32_e32 v153, 0xffff0000, v224
	v_lshlrev_b32_e32 v154, 16, v225
	v_and_b32_e32 v155, 0xffff0000, v225
	v_lshlrev_b32_e32 v156, 16, v226
	v_and_b32_e32 v157, 0xffff0000, v226
	v_lshlrev_b32_e32 v158, 16, v227
	v_and_b32_e32 v159, 0xffff0000, v227
	v_pk_add_f32 v[36:37], v[36:37], v[152:153]
	v_pk_add_f32 v[38:39], v[38:39], v[154:155]
	v_pk_add_f32 v[32:33], v[32:33], v[156:157]
	v_pk_add_f32 v[34:35], v[34:35], v[158:159]
	v_cvt_pk_bf16_f32 v132, v36, v37
	v_cvt_pk_bf16_f32 v133, v38, v39
	v_cvt_pk_bf16_f32 v134, v32, v33
	v_cvt_pk_bf16_f32 v135, v34, v35
	v_add_u32_e32 v138, 0xb0000, v131
	global_store_dwordx4 v138, v[132:135], s[54:55]
	s_waitcnt vmcnt(12)
	v_lshlrev_b32_e32 v152, 16, v228
	v_and_b32_e32 v153, 0xffff0000, v228
	v_lshlrev_b32_e32 v154, 16, v229
	v_and_b32_e32 v155, 0xffff0000, v229
	v_lshlrev_b32_e32 v156, 16, v230
	v_and_b32_e32 v157, 0xffff0000, v230
	v_lshlrev_b32_e32 v158, 16, v231
	v_and_b32_e32 v159, 0xffff0000, v231
	v_pk_mul_f32 v[28:29], v[28:29], v[152:153]
	v_pk_mul_f32 v[30:31], v[30:31], v[154:155]
	v_pk_mul_f32 v[24:25], v[24:25], v[156:157]
	v_pk_mul_f32 v[26:27], v[26:27], v[158:159]
	v_lshlrev_b32_e32 v152, 16, v232
	v_and_b32_e32 v153, 0xffff0000, v232
	v_lshlrev_b32_e32 v154, 16, v233
	v_and_b32_e32 v155, 0xffff0000, v233
	v_lshlrev_b32_e32 v156, 16, v234
	v_and_b32_e32 v157, 0xffff0000, v234
	v_lshlrev_b32_e32 v158, 16, v235
	v_and_b32_e32 v159, 0xffff0000, v235
	v_pk_add_f32 v[28:29], v[28:29], v[152:153]
	v_pk_add_f32 v[30:31], v[30:31], v[154:155]
	v_pk_add_f32 v[24:25], v[24:25], v[156:157]
	v_pk_add_f32 v[26:27], v[26:27], v[158:159]
	v_cvt_pk_bf16_f32 v132, v28, v29
	v_cvt_pk_bf16_f32 v133, v30, v31
	v_cvt_pk_bf16_f32 v134, v24, v25
	v_cvt_pk_bf16_f32 v135, v26, v27
	v_add_u32_e32 v138, 0x80100, v131
	global_store_dwordx4 v138, v[132:135], s[54:55]
	s_waitcnt vmcnt(10)
	v_lshlrev_b32_e32 v152, 16, v236
	v_and_b32_e32 v153, 0xffff0000, v236
	v_lshlrev_b32_e32 v154, 16, v237
	v_and_b32_e32 v155, 0xffff0000, v237
	v_lshlrev_b32_e32 v156, 16, v238
	v_and_b32_e32 v157, 0xffff0000, v238
	v_lshlrev_b32_e32 v158, 16, v239
	v_and_b32_e32 v159, 0xffff0000, v239
	v_pk_mul_f32 v[20:21], v[20:21], v[152:153]
	v_pk_mul_f32 v[22:23], v[22:23], v[154:155]
	v_pk_mul_f32 v[16:17], v[16:17], v[156:157]
	v_pk_mul_f32 v[18:19], v[18:19], v[158:159]
	v_lshlrev_b32_e32 v152, 16, v240
	v_and_b32_e32 v153, 0xffff0000, v240
	v_lshlrev_b32_e32 v154, 16, v241
	v_and_b32_e32 v155, 0xffff0000, v241
	v_lshlrev_b32_e32 v156, 16, v242
	v_and_b32_e32 v157, 0xffff0000, v242
	v_lshlrev_b32_e32 v158, 16, v243
	v_and_b32_e32 v159, 0xffff0000, v243
	v_pk_add_f32 v[20:21], v[20:21], v[152:153]
	v_pk_add_f32 v[22:23], v[22:23], v[154:155]
	v_pk_add_f32 v[16:17], v[16:17], v[156:157]
	v_pk_add_f32 v[18:19], v[18:19], v[158:159]
	v_cvt_pk_bf16_f32 v132, v20, v21
	v_cvt_pk_bf16_f32 v133, v22, v23
	v_cvt_pk_bf16_f32 v134, v16, v17
	v_cvt_pk_bf16_f32 v135, v18, v19
	v_add_u32_e32 v138, 0x90100, v131
	global_store_dwordx4 v138, v[132:135], s[54:55]
	s_waitcnt vmcnt(8)
	v_lshlrev_b32_e32 v152, 16, v188
	v_and_b32_e32 v153, 0xffff0000, v188
	v_lshlrev_b32_e32 v154, 16, v189
	v_and_b32_e32 v155, 0xffff0000, v189
	v_lshlrev_b32_e32 v156, 16, v190
	v_and_b32_e32 v157, 0xffff0000, v190
	v_lshlrev_b32_e32 v158, 16, v191
	v_and_b32_e32 v159, 0xffff0000, v191
	v_pk_mul_f32 v[12:13], v[12:13], v[152:153]
	v_pk_mul_f32 v[14:15], v[14:15], v[154:155]
	v_pk_mul_f32 v[8:9], v[8:9], v[156:157]
	v_pk_mul_f32 v[10:11], v[10:11], v[158:159]
	v_lshlrev_b32_e32 v152, 16, v192
	v_and_b32_e32 v153, 0xffff0000, v192
	v_lshlrev_b32_e32 v154, 16, v193
	v_and_b32_e32 v155, 0xffff0000, v193
	v_lshlrev_b32_e32 v156, 16, v194
	v_and_b32_e32 v157, 0xffff0000, v194
	v_lshlrev_b32_e32 v158, 16, v195
	v_and_b32_e32 v159, 0xffff0000, v195
	v_pk_add_f32 v[12:13], v[12:13], v[152:153]
	v_pk_add_f32 v[14:15], v[14:15], v[154:155]
	v_pk_add_f32 v[8:9], v[8:9], v[156:157]
	v_pk_add_f32 v[10:11], v[10:11], v[158:159]
	v_cvt_pk_bf16_f32 v132, v12, v13
	v_cvt_pk_bf16_f32 v133, v14, v15
	v_cvt_pk_bf16_f32 v134, v8, v9
	v_cvt_pk_bf16_f32 v135, v10, v11
	v_add_u32_e32 v138, 0xa0100, v131
	global_store_dwordx4 v138, v[132:135], s[54:55]
	s_waitcnt vmcnt(6)
	v_lshlrev_b32_e32 v152, 16, v196
	v_and_b32_e32 v153, 0xffff0000, v196
	v_lshlrev_b32_e32 v154, 16, v197
	v_and_b32_e32 v155, 0xffff0000, v197
	v_lshlrev_b32_e32 v156, 16, v198
	v_and_b32_e32 v157, 0xffff0000, v198
	v_lshlrev_b32_e32 v158, 16, v199
	v_and_b32_e32 v159, 0xffff0000, v199
	v_pk_mul_f32 v[4:5], v[4:5], v[152:153]
	v_pk_mul_f32 v[6:7], v[6:7], v[154:155]
	v_pk_mul_f32 v[0:1], v[0:1], v[156:157]
	v_pk_mul_f32 v[2:3], v[2:3], v[158:159]
	v_lshlrev_b32_e32 v152, 16, v200
	v_and_b32_e32 v153, 0xffff0000, v200
	v_lshlrev_b32_e32 v154, 16, v201
	v_and_b32_e32 v155, 0xffff0000, v201
	v_lshlrev_b32_e32 v156, 16, v202
	v_and_b32_e32 v157, 0xffff0000, v202
	v_lshlrev_b32_e32 v158, 16, v203
	v_and_b32_e32 v159, 0xffff0000, v203
	v_pk_add_f32 v[4:5], v[4:5], v[152:153]
	v_pk_add_f32 v[6:7], v[6:7], v[154:155]
	v_pk_add_f32 v[0:1], v[0:1], v[156:157]
	v_pk_add_f32 v[2:3], v[2:3], v[158:159]
	v_cvt_pk_bf16_f32 v132, v4, v5
	v_cvt_pk_bf16_f32 v133, v6, v7
	v_cvt_pk_bf16_f32 v134, v0, v1
	v_cvt_pk_bf16_f32 v135, v2, v3
	v_add_u32_e32 v138, 0xb0100, v131
	global_store_dwordx4 v138, v[132:135], s[54:55]
	s_branch .LBB0_562
; __device__ __forceinline__ unsigned cvt_pk_bf16(float lo, float hi) { unsigned r; asm("v_cvt_pk_bf16_f32 %0, %1, %2" : "=v"(r) : "v"(lo), "v"(hi)); return r; }
; __device__ __forceinline__ float sigmoidf_(float x) { return __builtin_amdgcn_rcpf(1.0f + __expf(-x)); }
;     __device__ __forceinline__ void operator()(f32x4 (&acc)[2][2][4][2], const GUnit& u, int wr, int wc, int fr, int fq, int tid) const {
;     ...
;         if ((sub & 1) == 0) {
;             const float* bp = bgate + br * 2048 + u.pn * BM + wc * 32 + 8 * fq;
; #pragma unroll
;             for (int ai = 0; ai < 2; ++ai)
; #pragma unroll
;                 for (int bj = 0; bj < 2; ++bj) { const f32x4 b0 = *(const f32x4*)(bp + bj * HALF), b1 = *(const f32x4*)(bp + bj * HALF + 4);
; #pragma unroll
;                     for (int m = 0; m < 4; ++m) { f32x4 v0 = acc[ai][bj][m][0] + b0, v1 = acc[ai][bj][m][1] + b1;
; #pragma unroll
;                         for (int j = 0; j < 4; ++j) { v0[j] = sigmoidf_(v0[j]); v1[j] = sigmoidf_(v1[j]); }
;                         u32x4 w; w.x = cvt_pk_bf16(v0[0], v0[1]); w.y = cvt_pk_bf16(v0[2], v0[3]); w.z = cvt_pk_bf16(v1[0], v1[1]); w.w = cvt_pk_bf16(v1[2], v1[3]);
;                         st_coh16(gp, w); gp += 4096; asm volatile("" : "+v"(gp) :: "memory"); } }
.LBB0_679:
	s_and_b64 vcc, exec, s[12:13]
	s_cbranch_vccz .LBB0_562
	s_lshl_b32 s12, s96, 10
	s_ashr_i32 s13, s12, 31
	s_lshl_b64 s[12:13], s[12:13], 2
	v_readlane_b32 s14, v254, 50
	s_add_u32 s14, s14, s12
	v_readlane_b32 s12, v255, 21
	s_addc_u32 s15, s12, s13
	s_lshl_b32 s12, s97, 8
	s_ashr_i32 s13, s12, 31
	s_lshl_b64 s[12:13], s[12:13], 2
	s_add_u32 s12, s14, s12
	s_addc_u32 s13, s15, s13
	s_lshl_b32 s14, s20, 2
	s_add_u32 s12, s12, s14
	v_lshlrev_b32_e32 v128, 3, v136
	s_addc_u32 s13, s13, 0
	v_ashrrev_i32_e32 v129, 31, v128
	v_lshl_add_u64 v[152:153], v[128:129], 2, s[12:13]
	global_load_dwordx4 v[128:131], v[152:153], off offset:16
	global_load_dwordx4 v[132:135], v[152:153], off
	s_waitcnt vmcnt(0)
	v_pk_add_f32 v[122:123], v[122:123], v[130:131]
	v_pk_add_f32 v[120:121], v[120:121], v[128:129]
	v_mul_f32_e32 v122, 0xbfb8aa3b, v122
	v_mul_f32_e32 v120, 0xbfb8aa3b, v120
	v_mul_f32_e32 v121, 0xbfb8aa3b, v121
	v_exp_f32_e32 v120, v120
	v_exp_f32_e32 v121, v121
	v_exp_f32_e32 v122, v122
	v_pk_add_f32 v[126:127], v[126:127], v[134:135]
	v_pk_add_f32 v[124:125], v[124:125], v[132:133]
	v_add_f32_e32 v120, 1.0, v120
	v_add_f32_e32 v121, 1.0, v121
	v_add_f32_e32 v122, 1.0, v122
	v_rcp_f32_e32 v136, v120
	v_mul_f32_e32 v120, 0xbfb8aa3b, v125
	v_rcp_f32_e32 v125, v121
	v_mul_f32_e32 v121, 0xbfb8aa3b, v126
	v_rcp_f32_e32 v126, v122
	v_mul_f32_e32 v122, 0xbfb8aa3b, v127
	v_mul_f32_e32 v124, 0xbfb8aa3b, v124
	v_exp_f32_e32 v120, v120
	v_exp_f32_e32 v121, v121
	v_exp_f32_e32 v122, v122
	v_mul_f32_e32 v123, 0xbfb8aa3b, v123
	v_pk_add_f32 v[114:115], v[114:115], v[130:131]
	v_pk_add_f32 v[112:113], v[112:113], v[128:129]
	v_exp_f32_e32 v124, v124
	v_exp_f32_e32 v123, v123
	v_mul_f32_e32 v112, 0xbfb8aa3b, v112
	v_mul_f32_e32 v113, 0xbfb8aa3b, v113
	v_mul_f32_e32 v114, 0xbfb8aa3b, v114
	v_exp_f32_e32 v112, v112
	v_exp_f32_e32 v113, v113
	v_exp_f32_e32 v114, v114
	v_add_f32_e32 v120, 1.0, v120
	v_add_f32_e32 v121, 1.0, v121
	v_add_f32_e32 v122, 1.0, v122
	v_add_f32_e32 v124, 1.0, v124
	v_rcp_f32_e32 v120, v120
	v_rcp_f32_e32 v121, v121
	v_rcp_f32_e32 v122, v122
	v_add_f32_e32 v123, 1.0, v123
	v_rcp_f32_e32 v124, v124
	v_rcp_f32_e32 v123, v123
	v_cvt_pk_bf16_f32 v120, v124, v120
	v_cvt_pk_bf16_f32 v121, v121, v122
	v_cvt_pk_bf16_f32 v122, v136, v125
	v_pk_add_f32 v[118:119], v[118:119], v[134:135]
	v_pk_add_f32 v[116:117], v[116:117], v[132:133]
	v_add_f32_e32 v112, 1.0, v112
	v_add_f32_e32 v113, 1.0, v113
	v_add_f32_e32 v114, 1.0, v114
	v_cvt_pk_bf16_f32 v123, v126, v123
	global_store_dwordx2 v[150:151], v[120:121], off sc1
	global_store_dwordx2 v[150:151], v[122:123], off offset:8 sc1
	v_rcp_f32_e32 v122, v112
	v_mul_f32_e32 v112, 0xbfb8aa3b, v117
	v_rcp_f32_e32 v117, v113
	v_mul_f32_e32 v113, 0xbfb8aa3b, v118
	v_rcp_f32_e32 v118, v114
	v_mul_f32_e32 v114, 0xbfb8aa3b, v119
	v_mul_f32_e32 v116, 0xbfb8aa3b, v116
	v_exp_f32_e32 v112, v112
	v_exp_f32_e32 v113, v113
	v_exp_f32_e32 v114, v114
	v_mul_f32_e32 v115, 0xbfb8aa3b, v115
	v_pk_add_f32 v[106:107], v[106:107], v[130:131]
	v_pk_add_f32 v[104:105], v[104:105], v[128:129]
	v_exp_f32_e32 v116, v116
	v_exp_f32_e32 v115, v115
	v_mul_f32_e32 v104, 0xbfb8aa3b, v104
	v_mul_f32_e32 v105, 0xbfb8aa3b, v105
	v_mul_f32_e32 v106, 0xbfb8aa3b, v106
	v_lshl_add_u64 v[120:121], v[150:151], 0, s[86:87]
	v_exp_f32_e32 v104, v104
	v_exp_f32_e32 v105, v105
	v_exp_f32_e32 v106, v106
	v_add_f32_e32 v112, 1.0, v112
	v_add_f32_e32 v113, 1.0, v113
	v_add_f32_e32 v114, 1.0, v114
	v_add_f32_e32 v116, 1.0, v116
	v_rcp_f32_e32 v112, v112
	v_rcp_f32_e32 v113, v113
	v_rcp_f32_e32 v114, v114
	v_add_f32_e32 v115, 1.0, v115
	v_rcp_f32_e32 v116, v116
	v_rcp_f32_e32 v115, v115
	v_cvt_pk_bf16_f32 v112, v116, v112
	v_cvt_pk_bf16_f32 v113, v113, v114
	v_cvt_pk_bf16_f32 v114, v122, v117
	v_pk_add_f32 v[110:111], v[110:111], v[134:135]
	v_pk_add_f32 v[108:109], v[108:109], v[132:133]
	v_add_f32_e32 v104, 1.0, v104
	v_add_f32_e32 v105, 1.0, v105
	v_add_f32_e32 v106, 1.0, v106
	v_cvt_pk_bf16_f32 v115, v118, v115
	flat_store_dwordx2 v[120:121], v[112:113] sc1
	flat_store_dwordx2 v[120:121], v[114:115] offset:8 sc1
	v_rcp_f32_e32 v114, v104
	v_mul_f32_e32 v104, 0xbfb8aa3b, v109
	v_rcp_f32_e32 v109, v105
	v_mul_f32_e32 v105, 0xbfb8aa3b, v110
	v_rcp_f32_e32 v110, v106
	v_mul_f32_e32 v106, 0xbfb8aa3b, v111
	v_mul_f32_e32 v108, 0xbfb8aa3b, v108
	v_exp_f32_e32 v104, v104
	v_exp_f32_e32 v105, v105
	v_exp_f32_e32 v106, v106
	v_mul_f32_e32 v107, 0xbfb8aa3b, v107
	v_pk_add_f32 v[96:97], v[96:97], v[128:129]
	v_exp_f32_e32 v108, v108
	v_exp_f32_e32 v107, v107
	v_pk_add_f32 v[98:99], v[98:99], v[130:131]
	v_mul_f32_e32 v96, 0xbfb8aa3b, v96
	v_mul_f32_e32 v97, 0xbfb8aa3b, v97
	v_lshl_add_u64 v[112:113], v[120:121], 0, s[86:87]
	v_exp_f32_e32 v96, v96
	v_exp_f32_e32 v97, v97
	v_mul_f32_e32 v98, 0xbfb8aa3b, v98
	v_exp_f32_e32 v98, v98
	v_add_f32_e32 v104, 1.0, v104
	v_add_f32_e32 v105, 1.0, v105
	v_add_f32_e32 v106, 1.0, v106
	v_add_f32_e32 v108, 1.0, v108
	v_rcp_f32_e32 v104, v104
	v_rcp_f32_e32 v105, v105
	v_rcp_f32_e32 v106, v106
	v_add_f32_e32 v107, 1.0, v107
	v_rcp_f32_e32 v108, v108
	v_rcp_f32_e32 v107, v107
	v_cvt_pk_bf16_f32 v104, v108, v104
	v_cvt_pk_bf16_f32 v105, v105, v106
	v_cvt_pk_bf16_f32 v106, v114, v109
	v_pk_add_f32 v[102:103], v[102:103], v[134:135]
	v_pk_add_f32 v[100:101], v[100:101], v[132:133]
	v_add_f32_e32 v96, 1.0, v96
	v_add_f32_e32 v97, 1.0, v97
	v_cvt_pk_bf16_f32 v107, v110, v107
	flat_store_dwordx2 v[112:113], v[104:105] sc1
	flat_store_dwordx2 v[112:113], v[106:107] offset:8 sc1
	v_rcp_f32_e32 v106, v96
	v_mul_f32_e32 v96, 0xbfb8aa3b, v101
	v_rcp_f32_e32 v101, v97
	v_mul_f32_e32 v97, 0xbfb8aa3b, v102
	v_add_f32_e32 v98, 1.0, v98
	v_mul_f32_e32 v100, 0xbfb8aa3b, v100
	v_exp_f32_e32 v96, v96
	v_exp_f32_e32 v97, v97
	v_rcp_f32_e32 v102, v98
	v_mul_f32_e32 v98, 0xbfb8aa3b, v103
	v_mul_f32_e32 v99, 0xbfb8aa3b, v99
	v_exp_f32_e32 v100, v100
	v_exp_f32_e32 v98, v98
	v_exp_f32_e32 v99, v99
	v_lshl_add_u64 v[104:105], v[112:113], 0, s[86:87]
	v_add_f32_e32 v96, 1.0, v96
	v_add_f32_e32 v97, 1.0, v97
	v_add_f32_e32 v100, 1.0, v100
	v_rcp_f32_e32 v96, v96
	v_rcp_f32_e32 v97, v97
	v_add_f32_e32 v98, 1.0, v98
	v_add_f32_e32 v99, 1.0, v99
	v_rcp_f32_e32 v100, v100
	v_rcp_f32_e32 v98, v98
	v_rcp_f32_e32 v99, v99
	v_cvt_pk_bf16_f32 v96, v100, v96
	v_cvt_pk_bf16_f32 v97, v97, v98
	v_cvt_pk_bf16_f32 v98, v106, v101
	v_cvt_pk_bf16_f32 v99, v102, v99
	flat_store_dwordx2 v[104:105], v[96:97] sc1
	flat_store_dwordx2 v[104:105], v[98:99] offset:8 sc1
	v_lshl_add_u64 v[104:105], v[104:105], 0, s[86:87]
	global_load_dwordx4 v[96:99], v[152:153], off offset:528
	global_load_dwordx4 v[100:103], v[152:153], off offset:512
	s_waitcnt vmcnt(0)
; __device__ __forceinline__ unsigned cvt_pk_bf16(float lo, float hi) { unsigned r; asm("v_cvt_pk_bf16_f32 %0, %1, %2" : "=v"(r) : "v"(lo), "v"(hi)); return r; }
; __device__ __forceinline__ float sigmoidf_(float x) { return __builtin_amdgcn_rcpf(1.0f + __expf(-x)); }
;     __device__ __forceinline__ void operator()(f32x4 (&acc)[2][2][4][2], const GUnit& u, int wr, int wc, int fr, int fq, int tid) const {
;     ...
;                 for (int bj = 0; bj < 2; ++bj) { const f32x4 b0 = *(const f32x4*)(bp + bj * HALF), b1 = *(const f32x4*)(bp + bj * HALF + 4);
; #pragma unroll
;                     for (int m = 0; m < 4; ++m) { f32x4 v0 = acc[ai][bj][m][0] + b0, v1 = acc[ai][bj][m][1] + b1;
; #pragma unroll
;                         for (int j = 0; j < 4; ++j) { v0[j] = sigmoidf_(v0[j]); v1[j] = sigmoidf_(v1[j]); }
;                         u32x4 w; w.x = cvt_pk_bf16(v0[0], v0[1]); w.y = cvt_pk_bf16(v0[2], v0[3]); w.z = cvt_pk_bf16(v1[0], v1[1]); w.w = cvt_pk_bf16(v1[2], v1[3]);
;                         st_coh16(gp, w); gp += 4096; asm volatile("" : "+v"(gp) :: "memory"); } }
	v_pk_add_f32 v[90:91], v[90:91], v[98:99]
	v_pk_add_f32 v[88:89], v[88:89], v[96:97]
	v_mul_f32_e32 v90, 0xbfb8aa3b, v90
	v_mul_f32_e32 v88, 0xbfb8aa3b, v88
	v_mul_f32_e32 v89, 0xbfb8aa3b, v89
	v_exp_f32_e32 v88, v88
	v_exp_f32_e32 v89, v89
	v_exp_f32_e32 v90, v90
	v_pk_add_f32 v[94:95], v[94:95], v[102:103]
	v_pk_add_f32 v[92:93], v[92:93], v[100:101]
	v_add_f32_e32 v88, 1.0, v88
	v_add_f32_e32 v89, 1.0, v89
	v_add_f32_e32 v90, 1.0, v90
	v_rcp_f32_e32 v106, v88
	v_mul_f32_e32 v88, 0xbfb8aa3b, v93
	v_rcp_f32_e32 v93, v89
	v_mul_f32_e32 v89, 0xbfb8aa3b, v94
	v_rcp_f32_e32 v94, v90
	v_mul_f32_e32 v90, 0xbfb8aa3b, v95
	v_mul_f32_e32 v92, 0xbfb8aa3b, v92
	v_exp_f32_e32 v88, v88
	v_exp_f32_e32 v89, v89
	v_exp_f32_e32 v90, v90
	v_mul_f32_e32 v91, 0xbfb8aa3b, v91
	v_pk_add_f32 v[82:83], v[82:83], v[98:99]
	v_pk_add_f32 v[80:81], v[80:81], v[96:97]
	v_exp_f32_e32 v92, v92
	v_exp_f32_e32 v91, v91
	v_mul_f32_e32 v80, 0xbfb8aa3b, v80
	v_mul_f32_e32 v81, 0xbfb8aa3b, v81
	v_mul_f32_e32 v82, 0xbfb8aa3b, v82
	v_exp_f32_e32 v80, v80
	v_exp_f32_e32 v81, v81
	v_exp_f32_e32 v82, v82
	v_add_f32_e32 v88, 1.0, v88
	v_add_f32_e32 v89, 1.0, v89
	v_add_f32_e32 v90, 1.0, v90
	v_add_f32_e32 v92, 1.0, v92
	v_rcp_f32_e32 v88, v88
	v_rcp_f32_e32 v89, v89
	v_rcp_f32_e32 v90, v90
	v_add_f32_e32 v91, 1.0, v91
	v_rcp_f32_e32 v92, v92
	v_rcp_f32_e32 v91, v91
	v_cvt_pk_bf16_f32 v88, v92, v88
	v_cvt_pk_bf16_f32 v89, v89, v90
	v_cvt_pk_bf16_f32 v90, v106, v93
	v_pk_add_f32 v[86:87], v[86:87], v[102:103]
	v_pk_add_f32 v[84:85], v[84:85], v[100:101]
	v_add_f32_e32 v80, 1.0, v80
	v_add_f32_e32 v81, 1.0, v81
	v_add_f32_e32 v82, 1.0, v82
	v_cvt_pk_bf16_f32 v91, v94, v91
	flat_store_dwordx2 v[104:105], v[88:89] sc1
	flat_store_dwordx2 v[104:105], v[90:91] offset:8 sc1
	v_rcp_f32_e32 v90, v80
	v_mul_f32_e32 v80, 0xbfb8aa3b, v85
	v_rcp_f32_e32 v85, v81
	v_mul_f32_e32 v81, 0xbfb8aa3b, v86
	v_rcp_f32_e32 v86, v82
	v_mul_f32_e32 v82, 0xbfb8aa3b, v87
	v_mul_f32_e32 v84, 0xbfb8aa3b, v84
	v_exp_f32_e32 v80, v80
	v_exp_f32_e32 v81, v81
	v_exp_f32_e32 v82, v82
	v_mul_f32_e32 v83, 0xbfb8aa3b, v83
	v_pk_add_f32 v[74:75], v[74:75], v[98:99]
	v_pk_add_f32 v[72:73], v[72:73], v[96:97]
	v_exp_f32_e32 v84, v84
	v_exp_f32_e32 v83, v83
	v_mul_f32_e32 v72, 0xbfb8aa3b, v72
	v_mul_f32_e32 v73, 0xbfb8aa3b, v73
	v_mul_f32_e32 v74, 0xbfb8aa3b, v74
	v_lshl_add_u64 v[88:89], v[104:105], 0, s[86:87]
	v_exp_f32_e32 v72, v72
	v_exp_f32_e32 v73, v73
	v_exp_f32_e32 v74, v74
	v_add_f32_e32 v80, 1.0, v80
	v_add_f32_e32 v81, 1.0, v81
	v_add_f32_e32 v82, 1.0, v82
	v_add_f32_e32 v84, 1.0, v84
	v_rcp_f32_e32 v80, v80
	v_rcp_f32_e32 v81, v81
	v_rcp_f32_e32 v82, v82
	v_add_f32_e32 v83, 1.0, v83
	v_rcp_f32_e32 v84, v84
	v_rcp_f32_e32 v83, v83
	v_cvt_pk_bf16_f32 v80, v84, v80
	v_cvt_pk_bf16_f32 v81, v81, v82
	v_cvt_pk_bf16_f32 v82, v90, v85
	v_pk_add_f32 v[78:79], v[78:79], v[102:103]
	v_pk_add_f32 v[76:77], v[76:77], v[100:101]
	v_add_f32_e32 v72, 1.0, v72
	v_add_f32_e32 v73, 1.0, v73
	v_add_f32_e32 v74, 1.0, v74
	v_cvt_pk_bf16_f32 v83, v86, v83
	flat_store_dwordx2 v[88:89], v[80:81] sc1
	flat_store_dwordx2 v[88:89], v[82:83] offset:8 sc1
	v_rcp_f32_e32 v82, v72
	v_mul_f32_e32 v72, 0xbfb8aa3b, v77
	v_rcp_f32_e32 v77, v73
	v_mul_f32_e32 v73, 0xbfb8aa3b, v78
	v_rcp_f32_e32 v78, v74
	v_mul_f32_e32 v74, 0xbfb8aa3b, v79
	v_mul_f32_e32 v76, 0xbfb8aa3b, v76
	v_exp_f32_e32 v72, v72
	v_exp_f32_e32 v73, v73
	v_exp_f32_e32 v74, v74
	v_mul_f32_e32 v75, 0xbfb8aa3b, v75
	v_pk_add_f32 v[64:65], v[64:65], v[96:97]
	v_exp_f32_e32 v76, v76
	v_exp_f32_e32 v75, v75
	v_pk_add_f32 v[66:67], v[66:67], v[98:99]
	v_mul_f32_e32 v64, 0xbfb8aa3b, v64
	v_mul_f32_e32 v65, 0xbfb8aa3b, v65
	v_lshl_add_u64 v[80:81], v[88:89], 0, s[86:87]
	v_exp_f32_e32 v64, v64
	v_exp_f32_e32 v65, v65
	v_mul_f32_e32 v66, 0xbfb8aa3b, v66
	v_exp_f32_e32 v66, v66
	v_add_f32_e32 v72, 1.0, v72
	v_add_f32_e32 v73, 1.0, v73
	v_add_f32_e32 v74, 1.0, v74
	v_add_f32_e32 v76, 1.0, v76
	v_rcp_f32_e32 v72, v72
	v_rcp_f32_e32 v73, v73
	v_rcp_f32_e32 v74, v74
	v_add_f32_e32 v75, 1.0, v75
	v_rcp_f32_e32 v76, v76
	v_rcp_f32_e32 v75, v75
	v_cvt_pk_bf16_f32 v72, v76, v72
	v_cvt_pk_bf16_f32 v73, v73, v74
	v_cvt_pk_bf16_f32 v74, v82, v77
	v_pk_add_f32 v[70:71], v[70:71], v[102:103]
	v_pk_add_f32 v[68:69], v[68:69], v[100:101]
	v_add_f32_e32 v64, 1.0, v64
	v_add_f32_e32 v65, 1.0, v65
	v_cvt_pk_bf16_f32 v75, v78, v75
	flat_store_dwordx2 v[80:81], v[72:73] sc1
	flat_store_dwordx2 v[80:81], v[74:75] offset:8 sc1
	v_rcp_f32_e32 v74, v64
	v_mul_f32_e32 v64, 0xbfb8aa3b, v69
	v_rcp_f32_e32 v69, v65
	v_mul_f32_e32 v65, 0xbfb8aa3b, v70
	v_add_f32_e32 v66, 1.0, v66
	v_mul_f32_e32 v68, 0xbfb8aa3b, v68
	v_exp_f32_e32 v64, v64
	v_exp_f32_e32 v65, v65
	v_rcp_f32_e32 v70, v66
	v_mul_f32_e32 v66, 0xbfb8aa3b, v71
	v_mul_f32_e32 v67, 0xbfb8aa3b, v67
	v_exp_f32_e32 v68, v68
	v_exp_f32_e32 v66, v66
	v_exp_f32_e32 v67, v67
	v_lshl_add_u64 v[72:73], v[80:81], 0, s[86:87]
	v_add_f32_e32 v64, 1.0, v64
	v_add_f32_e32 v65, 1.0, v65
	v_add_f32_e32 v68, 1.0, v68
	v_rcp_f32_e32 v64, v64
	v_rcp_f32_e32 v65, v65
	v_add_f32_e32 v66, 1.0, v66
	v_add_f32_e32 v67, 1.0, v67
	v_rcp_f32_e32 v68, v68
	v_rcp_f32_e32 v66, v66
	v_rcp_f32_e32 v67, v67
	v_cvt_pk_bf16_f32 v64, v68, v64
	v_cvt_pk_bf16_f32 v65, v65, v66
	v_cvt_pk_bf16_f32 v66, v74, v69
	v_cvt_pk_bf16_f32 v67, v70, v67
	flat_store_dwordx2 v[72:73], v[64:65] sc1
	flat_store_dwordx2 v[72:73], v[66:67] offset:8 sc1
	v_lshl_add_u64 v[72:73], v[72:73], 0, s[86:87]
	global_load_dwordx4 v[64:67], v[152:153], off offset:16
	global_load_dwordx4 v[68:71], v[152:153], off
	s_waitcnt vmcnt(0)
; __device__ __forceinline__ unsigned cvt_pk_bf16(float lo, float hi) { unsigned r; asm("v_cvt_pk_bf16_f32 %0, %1, %2" : "=v"(r) : "v"(lo), "v"(hi)); return r; }
; __device__ __forceinline__ float sigmoidf_(float x) { return __builtin_amdgcn_rcpf(1.0f + __expf(-x)); }
;     __device__ __forceinline__ void operator()(f32x4 (&acc)[2][2][4][2], const GUnit& u, int wr, int wc, int fr, int fq, int tid) const {
;     ...
;                 for (int bj = 0; bj < 2; ++bj) { const f32x4 b0 = *(const f32x4*)(bp + bj * HALF), b1 = *(const f32x4*)(bp + bj * HALF + 4);
; #pragma unroll
;                     for (int m = 0; m < 4; ++m) { f32x4 v0 = acc[ai][bj][m][0] + b0, v1 = acc[ai][bj][m][1] + b1;
; #pragma unroll
;                         for (int j = 0; j < 4; ++j) { v0[j] = sigmoidf_(v0[j]); v1[j] = sigmoidf_(v1[j]); }
;                         u32x4 w; w.x = cvt_pk_bf16(v0[0], v0[1]); w.y = cvt_pk_bf16(v0[2], v0[3]); w.z = cvt_pk_bf16(v1[0], v1[1]); w.w = cvt_pk_bf16(v1[2], v1[3]);
;                         st_coh16(gp, w); gp += 4096; asm volatile("" : "+v"(gp) :: "memory"); } }
	v_pk_add_f32 v[58:59], v[58:59], v[66:67]
	v_pk_add_f32 v[56:57], v[56:57], v[64:65]
	v_mul_f32_e32 v58, 0xbfb8aa3b, v58
	v_mul_f32_e32 v56, 0xbfb8aa3b, v56
	v_mul_f32_e32 v57, 0xbfb8aa3b, v57
	v_exp_f32_e32 v56, v56
	v_exp_f32_e32 v57, v57
	v_exp_f32_e32 v58, v58
	v_pk_add_f32 v[62:63], v[62:63], v[70:71]
	v_pk_add_f32 v[60:61], v[60:61], v[68:69]
	v_add_f32_e32 v56, 1.0, v56
	v_add_f32_e32 v57, 1.0, v57
	v_add_f32_e32 v58, 1.0, v58
	v_rcp_f32_e32 v74, v56
	v_mul_f32_e32 v56, 0xbfb8aa3b, v61
	v_rcp_f32_e32 v61, v57
	v_mul_f32_e32 v57, 0xbfb8aa3b, v62
	v_rcp_f32_e32 v62, v58
	v_mul_f32_e32 v58, 0xbfb8aa3b, v63
	v_mul_f32_e32 v60, 0xbfb8aa3b, v60
	v_exp_f32_e32 v56, v56
	v_exp_f32_e32 v57, v57
	v_exp_f32_e32 v58, v58
	v_mul_f32_e32 v59, 0xbfb8aa3b, v59
	v_pk_add_f32 v[50:51], v[50:51], v[66:67]
	v_pk_add_f32 v[48:49], v[48:49], v[64:65]
	v_exp_f32_e32 v60, v60
	v_exp_f32_e32 v59, v59
	v_mul_f32_e32 v48, 0xbfb8aa3b, v48
	v_mul_f32_e32 v49, 0xbfb8aa3b, v49
	v_mul_f32_e32 v50, 0xbfb8aa3b, v50
	v_exp_f32_e32 v48, v48
	v_exp_f32_e32 v49, v49
	v_exp_f32_e32 v50, v50
	v_add_f32_e32 v56, 1.0, v56
	v_add_f32_e32 v57, 1.0, v57
	v_add_f32_e32 v58, 1.0, v58
	v_add_f32_e32 v60, 1.0, v60
	v_rcp_f32_e32 v56, v56
	v_rcp_f32_e32 v57, v57
	v_rcp_f32_e32 v58, v58
	v_add_f32_e32 v59, 1.0, v59
	v_rcp_f32_e32 v60, v60
	v_rcp_f32_e32 v59, v59
	v_cvt_pk_bf16_f32 v56, v60, v56
	v_cvt_pk_bf16_f32 v57, v57, v58
	v_cvt_pk_bf16_f32 v58, v74, v61
	v_pk_add_f32 v[54:55], v[54:55], v[70:71]
	v_pk_add_f32 v[52:53], v[52:53], v[68:69]
	v_add_f32_e32 v48, 1.0, v48
	v_add_f32_e32 v49, 1.0, v49
	v_add_f32_e32 v50, 1.0, v50
	v_cvt_pk_bf16_f32 v59, v62, v59
	flat_store_dwordx2 v[72:73], v[56:57] sc1
	flat_store_dwordx2 v[72:73], v[58:59] offset:8 sc1
	v_rcp_f32_e32 v58, v48
	v_mul_f32_e32 v48, 0xbfb8aa3b, v53
	v_rcp_f32_e32 v53, v49
	v_mul_f32_e32 v49, 0xbfb8aa3b, v54
	v_rcp_f32_e32 v54, v50
	v_mul_f32_e32 v50, 0xbfb8aa3b, v55
	v_mul_f32_e32 v52, 0xbfb8aa3b, v52
	v_exp_f32_e32 v48, v48
	v_exp_f32_e32 v49, v49
	v_exp_f32_e32 v50, v50
	v_mul_f32_e32 v51, 0xbfb8aa3b, v51
	v_pk_add_f32 v[42:43], v[42:43], v[66:67]
	v_pk_add_f32 v[40:41], v[40:41], v[64:65]
	v_exp_f32_e32 v52, v52
	v_exp_f32_e32 v51, v51
	v_mul_f32_e32 v40, 0xbfb8aa3b, v40
	v_mul_f32_e32 v41, 0xbfb8aa3b, v41
	v_mul_f32_e32 v42, 0xbfb8aa3b, v42
	v_lshl_add_u64 v[56:57], v[72:73], 0, s[86:87]
	v_exp_f32_e32 v40, v40
	v_exp_f32_e32 v41, v41
	v_exp_f32_e32 v42, v42
	v_add_f32_e32 v48, 1.0, v48
	v_add_f32_e32 v49, 1.0, v49
	v_add_f32_e32 v50, 1.0, v50
	v_add_f32_e32 v52, 1.0, v52
	v_rcp_f32_e32 v48, v48
	v_rcp_f32_e32 v49, v49
	v_rcp_f32_e32 v50, v50
	v_add_f32_e32 v51, 1.0, v51
	v_rcp_f32_e32 v52, v52
	v_rcp_f32_e32 v51, v51
	v_cvt_pk_bf16_f32 v48, v52, v48
	v_cvt_pk_bf16_f32 v49, v49, v50
	v_cvt_pk_bf16_f32 v50, v58, v53
	v_pk_add_f32 v[46:47], v[46:47], v[70:71]
	v_pk_add_f32 v[44:45], v[44:45], v[68:69]
	v_add_f32_e32 v40, 1.0, v40
	v_add_f32_e32 v41, 1.0, v41
	v_add_f32_e32 v42, 1.0, v42
	v_cvt_pk_bf16_f32 v51, v54, v51
	flat_store_dwordx2 v[56:57], v[48:49] sc1
	flat_store_dwordx2 v[56:57], v[50:51] offset:8 sc1
	v_rcp_f32_e32 v50, v40
	v_mul_f32_e32 v40, 0xbfb8aa3b, v45
	v_rcp_f32_e32 v45, v41
	v_mul_f32_e32 v41, 0xbfb8aa3b, v46
	v_rcp_f32_e32 v46, v42
	v_mul_f32_e32 v42, 0xbfb8aa3b, v47
	v_mul_f32_e32 v44, 0xbfb8aa3b, v44
	v_exp_f32_e32 v40, v40
	v_exp_f32_e32 v41, v41
	v_exp_f32_e32 v42, v42
	v_mul_f32_e32 v43, 0xbfb8aa3b, v43
	v_pk_add_f32 v[32:33], v[32:33], v[64:65]
	v_exp_f32_e32 v44, v44
	v_exp_f32_e32 v43, v43
	v_pk_add_f32 v[34:35], v[34:35], v[66:67]
	v_mul_f32_e32 v32, 0xbfb8aa3b, v32
	v_mul_f32_e32 v33, 0xbfb8aa3b, v33
	v_lshl_add_u64 v[48:49], v[56:57], 0, s[86:87]
	v_exp_f32_e32 v32, v32
	v_exp_f32_e32 v33, v33
	v_mul_f32_e32 v34, 0xbfb8aa3b, v34
	v_exp_f32_e32 v34, v34
	v_add_f32_e32 v40, 1.0, v40
	v_add_f32_e32 v41, 1.0, v41
	v_add_f32_e32 v42, 1.0, v42
	v_add_f32_e32 v44, 1.0, v44
	v_rcp_f32_e32 v40, v40
	v_rcp_f32_e32 v41, v41
	v_rcp_f32_e32 v42, v42
	v_add_f32_e32 v43, 1.0, v43
	v_rcp_f32_e32 v44, v44
	v_rcp_f32_e32 v43, v43
	v_cvt_pk_bf16_f32 v40, v44, v40
	v_cvt_pk_bf16_f32 v41, v41, v42
	v_cvt_pk_bf16_f32 v42, v50, v45
	v_pk_add_f32 v[38:39], v[38:39], v[70:71]
	v_pk_add_f32 v[36:37], v[36:37], v[68:69]
	v_add_f32_e32 v32, 1.0, v32
	v_add_f32_e32 v33, 1.0, v33
	v_cvt_pk_bf16_f32 v43, v46, v43
	flat_store_dwordx2 v[48:49], v[40:41] sc1
	flat_store_dwordx2 v[48:49], v[42:43] offset:8 sc1
	v_rcp_f32_e32 v42, v32
	v_mul_f32_e32 v32, 0xbfb8aa3b, v37
	v_rcp_f32_e32 v37, v33
	v_mul_f32_e32 v33, 0xbfb8aa3b, v38
	v_add_f32_e32 v34, 1.0, v34
	v_mul_f32_e32 v36, 0xbfb8aa3b, v36
	v_exp_f32_e32 v32, v32
	v_exp_f32_e32 v33, v33
	v_rcp_f32_e32 v38, v34
	v_mul_f32_e32 v34, 0xbfb8aa3b, v39
	v_mul_f32_e32 v35, 0xbfb8aa3b, v35
	v_exp_f32_e32 v36, v36
	v_exp_f32_e32 v34, v34
	v_exp_f32_e32 v35, v35
	v_lshl_add_u64 v[40:41], v[48:49], 0, s[86:87]
	v_add_f32_e32 v32, 1.0, v32
	v_add_f32_e32 v33, 1.0, v33
	v_add_f32_e32 v36, 1.0, v36
	v_rcp_f32_e32 v32, v32
	v_rcp_f32_e32 v33, v33
	v_add_f32_e32 v34, 1.0, v34
	v_add_f32_e32 v35, 1.0, v35
	v_rcp_f32_e32 v36, v36
	v_rcp_f32_e32 v34, v34
	v_rcp_f32_e32 v35, v35
	v_cvt_pk_bf16_f32 v32, v36, v32
	v_cvt_pk_bf16_f32 v33, v33, v34
	v_cvt_pk_bf16_f32 v34, v42, v37
	v_cvt_pk_bf16_f32 v35, v38, v35
	flat_store_dwordx2 v[40:41], v[32:33] sc1
	flat_store_dwordx2 v[40:41], v[34:35] offset:8 sc1
	v_lshl_add_u64 v[40:41], v[40:41], 0, s[86:87]
	global_load_dwordx4 v[32:35], v[152:153], off offset:528
	global_load_dwordx4 v[36:39], v[152:153], off offset:512
	s_waitcnt vmcnt(0)
; __device__ __forceinline__ unsigned cvt_pk_bf16(float lo, float hi) { unsigned r; asm("v_cvt_pk_bf16_f32 %0, %1, %2" : "=v"(r) : "v"(lo), "v"(hi)); return r; }
; __device__ __forceinline__ float sigmoidf_(float x) { return __builtin_amdgcn_rcpf(1.0f + __expf(-x)); }
; #define PG8_WAIT_V(n) asm volatile("s_waitcnt vmcnt(" #n ")" ::: "memory")
; #define PG8_BAR __builtin_amdgcn_s_barrier()
;     __device__ __forceinline__ void operator()(f32x4 (&acc)[2][2][4][2], const GUnit& u, int wr, int wc, int fr, int fq, int tid) const {
;     ...
;                 for (int bj = 0; bj < 2; ++bj) { const f32x4 b0 = *(const f32x4*)(bp + bj * HALF), b1 = *(const f32x4*)(bp + bj * HALF + 4);
; #pragma unroll
;                     for (int m = 0; m < 4; ++m) { f32x4 v0 = acc[ai][bj][m][0] + b0, v1 = acc[ai][bj][m][1] + b1;
; #pragma unroll
;                         for (int j = 0; j < 4; ++j) { v0[j] = sigmoidf_(v0[j]); v1[j] = sigmoidf_(v1[j]); }
;                         u32x4 w; w.x = cvt_pk_bf16(v0[0], v0[1]); w.y = cvt_pk_bf16(v0[2], v0[3]); w.z = cvt_pk_bf16(v1[0], v1[1]); w.w = cvt_pk_bf16(v1[2], v1[3]);
;                         st_coh16(gp, w); gp += 4096; asm volatile("" : "+v"(gp) :: "memory"); } }
; template <class Epi, class Sched>
; __device__ __forceinline__ void gemm_phase(LAS unsigned char* lds, const Sched& S, const Epi& E) {
;     ...
;     PG8_WAIT_V(0);
;     if (wr == 0) PG8_BAR;
;     PG8_BAR;
	v_pk_add_f32 v[26:27], v[26:27], v[34:35]
	v_pk_add_f32 v[24:25], v[24:25], v[32:33]
	v_mul_f32_e32 v26, 0xbfb8aa3b, v26
	v_mul_f32_e32 v24, 0xbfb8aa3b, v24
	v_mul_f32_e32 v25, 0xbfb8aa3b, v25
	v_exp_f32_e32 v24, v24
	v_exp_f32_e32 v25, v25
	v_exp_f32_e32 v26, v26
	v_pk_add_f32 v[30:31], v[30:31], v[38:39]
	v_pk_add_f32 v[28:29], v[28:29], v[36:37]
	v_add_f32_e32 v24, 1.0, v24
	v_add_f32_e32 v25, 1.0, v25
	v_add_f32_e32 v26, 1.0, v26
	v_rcp_f32_e32 v42, v24
	v_mul_f32_e32 v24, 0xbfb8aa3b, v29
	v_rcp_f32_e32 v29, v25
	v_mul_f32_e32 v25, 0xbfb8aa3b, v30
	v_rcp_f32_e32 v30, v26
	v_mul_f32_e32 v26, 0xbfb8aa3b, v31
	v_mul_f32_e32 v28, 0xbfb8aa3b, v28
	v_exp_f32_e32 v24, v24
	v_exp_f32_e32 v25, v25
	v_exp_f32_e32 v26, v26
	v_mul_f32_e32 v27, 0xbfb8aa3b, v27
	v_pk_add_f32 v[18:19], v[18:19], v[34:35]
	v_pk_add_f32 v[16:17], v[16:17], v[32:33]
	v_exp_f32_e32 v28, v28
	v_exp_f32_e32 v27, v27
	v_mul_f32_e32 v16, 0xbfb8aa3b, v16
	v_mul_f32_e32 v17, 0xbfb8aa3b, v17
	v_mul_f32_e32 v18, 0xbfb8aa3b, v18
	v_exp_f32_e32 v16, v16
	v_exp_f32_e32 v17, v17
	v_exp_f32_e32 v18, v18
	v_add_f32_e32 v24, 1.0, v24
	v_add_f32_e32 v25, 1.0, v25
	v_add_f32_e32 v26, 1.0, v26
	v_add_f32_e32 v28, 1.0, v28
	v_rcp_f32_e32 v24, v24
	v_rcp_f32_e32 v25, v25
	v_rcp_f32_e32 v26, v26
	v_add_f32_e32 v27, 1.0, v27
	v_rcp_f32_e32 v28, v28
	v_rcp_f32_e32 v27, v27
	v_cvt_pk_bf16_f32 v24, v28, v24
	v_cvt_pk_bf16_f32 v25, v25, v26
	v_cvt_pk_bf16_f32 v26, v42, v29
	v_pk_add_f32 v[22:23], v[22:23], v[38:39]
	v_pk_add_f32 v[20:21], v[20:21], v[36:37]
	v_add_f32_e32 v16, 1.0, v16
	v_add_f32_e32 v17, 1.0, v17
	v_add_f32_e32 v18, 1.0, v18
	v_cvt_pk_bf16_f32 v27, v30, v27
	flat_store_dwordx2 v[40:41], v[24:25] sc1
	flat_store_dwordx2 v[40:41], v[26:27] offset:8 sc1
	v_rcp_f32_e32 v26, v16
	v_mul_f32_e32 v16, 0xbfb8aa3b, v21
	v_rcp_f32_e32 v21, v17
	v_mul_f32_e32 v17, 0xbfb8aa3b, v22
	v_rcp_f32_e32 v22, v18
	v_mul_f32_e32 v18, 0xbfb8aa3b, v23
	v_mul_f32_e32 v20, 0xbfb8aa3b, v20
	v_exp_f32_e32 v16, v16
	v_exp_f32_e32 v17, v17
	v_exp_f32_e32 v18, v18
	v_mul_f32_e32 v19, 0xbfb8aa3b, v19
	v_pk_add_f32 v[10:11], v[10:11], v[34:35]
	v_pk_add_f32 v[8:9], v[8:9], v[32:33]
	v_exp_f32_e32 v20, v20
	v_exp_f32_e32 v19, v19
	v_mul_f32_e32 v8, 0xbfb8aa3b, v8
	v_mul_f32_e32 v9, 0xbfb8aa3b, v9
	v_mul_f32_e32 v10, 0xbfb8aa3b, v10
	v_lshl_add_u64 v[24:25], v[40:41], 0, s[86:87]
	v_exp_f32_e32 v8, v8
	v_exp_f32_e32 v9, v9
	v_exp_f32_e32 v10, v10
	v_add_f32_e32 v16, 1.0, v16
	v_add_f32_e32 v17, 1.0, v17
	v_add_f32_e32 v18, 1.0, v18
	v_add_f32_e32 v20, 1.0, v20
	v_rcp_f32_e32 v16, v16
	v_rcp_f32_e32 v17, v17
	v_rcp_f32_e32 v18, v18
	v_add_f32_e32 v19, 1.0, v19
	v_rcp_f32_e32 v20, v20
	v_rcp_f32_e32 v19, v19
	v_cvt_pk_bf16_f32 v16, v20, v16
	v_cvt_pk_bf16_f32 v17, v17, v18
	v_cvt_pk_bf16_f32 v18, v26, v21
	v_pk_add_f32 v[14:15], v[14:15], v[38:39]
	v_pk_add_f32 v[12:13], v[12:13], v[36:37]
	v_add_f32_e32 v8, 1.0, v8
	v_add_f32_e32 v9, 1.0, v9
	v_add_f32_e32 v10, 1.0, v10
	v_cvt_pk_bf16_f32 v19, v22, v19
	flat_store_dwordx2 v[24:25], v[16:17] sc1
	flat_store_dwordx2 v[24:25], v[18:19] offset:8 sc1
	v_rcp_f32_e32 v18, v8
	v_mul_f32_e32 v8, 0xbfb8aa3b, v13
	v_rcp_f32_e32 v13, v9
	v_mul_f32_e32 v9, 0xbfb8aa3b, v14
	v_rcp_f32_e32 v14, v10
	v_mul_f32_e32 v10, 0xbfb8aa3b, v15
	v_mul_f32_e32 v12, 0xbfb8aa3b, v12
	v_exp_f32_e32 v8, v8
	v_exp_f32_e32 v9, v9
	v_exp_f32_e32 v10, v10
	v_mul_f32_e32 v11, 0xbfb8aa3b, v11
	v_pk_add_f32 v[0:1], v[0:1], v[32:33]
	v_exp_f32_e32 v12, v12
	v_exp_f32_e32 v11, v11
	v_pk_add_f32 v[2:3], v[2:3], v[34:35]
	v_mul_f32_e32 v0, 0xbfb8aa3b, v0
	v_mul_f32_e32 v1, 0xbfb8aa3b, v1
	v_lshl_add_u64 v[16:17], v[24:25], 0, s[86:87]
	v_exp_f32_e32 v0, v0
	v_exp_f32_e32 v1, v1
	v_mul_f32_e32 v2, 0xbfb8aa3b, v2
	v_exp_f32_e32 v2, v2
	v_add_f32_e32 v8, 1.0, v8
	v_add_f32_e32 v9, 1.0, v9
	v_add_f32_e32 v10, 1.0, v10
	v_add_f32_e32 v12, 1.0, v12
	v_rcp_f32_e32 v8, v8
	v_rcp_f32_e32 v9, v9
	v_rcp_f32_e32 v10, v10
	v_add_f32_e32 v11, 1.0, v11
	v_rcp_f32_e32 v12, v12
	v_rcp_f32_e32 v11, v11
	v_cvt_pk_bf16_f32 v8, v12, v8
	v_cvt_pk_bf16_f32 v9, v9, v10
	v_cvt_pk_bf16_f32 v10, v18, v13
	v_pk_add_f32 v[6:7], v[6:7], v[38:39]
	v_pk_add_f32 v[4:5], v[4:5], v[36:37]
	v_add_f32_e32 v0, 1.0, v0
	v_add_f32_e32 v1, 1.0, v1
	v_cvt_pk_bf16_f32 v11, v14, v11
	flat_store_dwordx2 v[16:17], v[8:9] sc1
	flat_store_dwordx2 v[16:17], v[10:11] offset:8 sc1
	v_rcp_f32_e32 v10, v0
	v_mul_f32_e32 v0, 0xbfb8aa3b, v5
	v_rcp_f32_e32 v5, v1
	v_mul_f32_e32 v1, 0xbfb8aa3b, v6
	v_add_f32_e32 v2, 1.0, v2
	v_mul_f32_e32 v4, 0xbfb8aa3b, v4
	v_exp_f32_e32 v0, v0
	v_exp_f32_e32 v1, v1
	v_rcp_f32_e32 v6, v2
	v_mul_f32_e32 v2, 0xbfb8aa3b, v7
	v_mul_f32_e32 v3, 0xbfb8aa3b, v3
	v_exp_f32_e32 v4, v4
	v_exp_f32_e32 v2, v2
	v_exp_f32_e32 v3, v3
	v_lshl_add_u64 v[8:9], v[16:17], 0, s[86:87]
	v_add_f32_e32 v0, 1.0, v0
	v_add_f32_e32 v1, 1.0, v1
	v_add_f32_e32 v4, 1.0, v4
	v_rcp_f32_e32 v0, v0
	v_rcp_f32_e32 v1, v1
	v_add_f32_e32 v2, 1.0, v2
	v_add_f32_e32 v3, 1.0, v3
	v_rcp_f32_e32 v4, v4
	v_rcp_f32_e32 v2, v2
	v_rcp_f32_e32 v3, v3
	v_cvt_pk_bf16_f32 v0, v4, v0
	v_cvt_pk_bf16_f32 v1, v1, v2
	v_cvt_pk_bf16_f32 v2, v10, v5
	v_cvt_pk_bf16_f32 v3, v6, v3
	flat_store_dwordx2 v[8:9], v[0:1] sc1
	flat_store_dwordx2 v[8:9], v[2:3] offset:8 sc1
	v_lshl_add_u64 v[0:1], v[8:9], 0, s[86:87]
	s_branch .LBB0_562
.LBB0_709:
	s_waitcnt vmcnt(0)
	v_readlane_b32 s3, v255, 31
	s_cmpk_gt_u32 s3, 0xff
	v_readlane_b32 s96, v255, 11
	v_readlane_b32 s64, v255, 15
	s_mov_b64 s[42:43], s[80:81]
	v_readlane_b32 s65, v255, 16
	s_cbranch_scc1 .LBB0_711
	s_barrier
